# memory cross-attention slab loops: 16 2-byte output stores per slab merged into 8 dword stores (DPP neighbour + v_perm pack, row pairs)
# baseline (speedup 1.0000x reference)
.LBB0_643:
	v_lshl_add_u64 v[8:9], v[100:101], 0, v[98:99]
	v_add_co_u32_e32 v12, vcc, 0x1b400000, v8
	ds_read_b128 v[0:3], v105
	ds_read_b128 v[4:7], v105 offset:64
	v_addc_co_u32_e32 v13, vcc, 0, v9, vcc
	flat_load_dwordx4 v[8:11], v[12:13] offset:1536
	flat_load_dwordx4 v[32:35], v[12:13] offset:1600
	ds_read_b128 v[12:15], v106
	ds_read_b128 v[16:19], v106 offset:64
	ds_read_b128 v[20:23], v107
	ds_read_b128 v[24:27], v107 offset:64
	ds_read_b128 v[28:31], v108
	ds_read_b128 v[68:71], v108 offset:64
	ds_read_b128 v[36:39], v105 offset:9216
	ds_read_b128 v[112:115], v105 offset:9280
	v_mov_b32_e32 v111, 0
	v_add_u32_e32 v96, s34, v96
	s_waitcnt vmcnt(0) lgkmcnt(0)
	v_mfma_f32_16x16x32_bf16 v[116:119], v[8:11], v[36:39], 0
	ds_read_b128 v[36:39], v105 offset:11520
	ds_read_b128 v[120:123], v105 offset:11584
	s_waitcnt lgkmcnt(1)
	v_mfma_f32_16x16x32_bf16 v[124:127], v[8:11], v[36:39], 0
	ds_read_b128 v[36:39], v105 offset:13824
	ds_read_b128 v[128:131], v105 offset:13888
	s_waitcnt lgkmcnt(1)
	v_mfma_f32_16x16x32_bf16 v[132:135], v[8:11], v[36:39], 0
	ds_read_b128 v[36:39], v105 offset:16128
	ds_read_b128 v[136:139], v105 offset:16192
	s_waitcnt lgkmcnt(1)
	v_mfma_f32_16x16x32_bf16 v[140:143], v[8:11], v[36:39], 0
	ds_read_b128 v[36:39], v105 offset:18432
	ds_read_b128 v[144:147], v105 offset:18496
	s_waitcnt lgkmcnt(1)
	v_mfma_f32_16x16x32_bf16 v[148:151], v[8:11], v[36:39], 0
	ds_read_b128 v[36:39], v105 offset:20736
	ds_read_b128 v[72:75], v105 offset:20800
	s_waitcnt lgkmcnt(1)
	v_mfma_f32_16x16x32_bf16 v[92:95], v[8:11], v[36:39], 0
	ds_read_b128 v[36:39], v105 offset:23040
	ds_read_b128 v[76:79], v105 offset:23104
	s_waitcnt lgkmcnt(1)
	v_mfma_f32_16x16x32_bf16 v[88:91], v[8:11], v[36:39], 0
	ds_read_b128 v[36:39], v105 offset:25344
	ds_read_b128 v[80:83], v105 offset:25408
	v_mfma_f32_16x16x32_bf16 v[0:3], v[8:11], v[0:3], 0
	v_mfma_f32_16x16x32_bf16 v[12:15], v[8:11], v[12:15], 0
	s_waitcnt lgkmcnt(1)
	v_mfma_f32_16x16x32_bf16 v[84:87], v[8:11], v[36:39], 0
	ds_read_b128 v[40:43], v105 offset:27648
	ds_read_b128 v[36:39], v105 offset:27712
	ds_read_b128 v[48:51], v105 offset:29952
	ds_read_b128 v[44:47], v105 offset:30016
	ds_read_b128 v[56:59], v105 offset:32256
	ds_read_b128 v[52:55], v105 offset:32320
	v_mfma_f32_16x16x32_bf16 v[20:23], v[8:11], v[20:23], 0
	ds_read_b128 v[64:67], v105 offset:34560
	ds_read_b128 v[60:63], v105 offset:34624
	v_mfma_f32_16x16x32_bf16 v[28:31], v[8:11], v[28:31], 0
	s_waitcnt lgkmcnt(5)
	v_mfma_f32_16x16x32_bf16 v[48:51], v[8:11], v[48:51], 0
	s_waitcnt lgkmcnt(3)
	v_mfma_f32_16x16x32_bf16 v[56:59], v[8:11], v[56:59], 0
	v_mfma_f32_16x16x32_bf16 v[0:3], v[32:35], v[4:7], v[0:3]
	v_mfma_f32_16x16x32_bf16 v[4:7], v[32:35], v[16:19], v[12:15]
	v_mfma_f32_16x16x32_bf16 v[40:43], v[8:11], v[40:43], 0
	s_waitcnt lgkmcnt(1)
	v_mfma_f32_16x16x32_bf16 v[64:67], v[8:11], v[64:67], 0
	v_mfma_f32_16x16x32_bf16 v[8:11], v[32:35], v[24:27], v[20:23]
	v_mfma_f32_16x16x32_bf16 v[12:15], v[32:35], v[68:71], v[28:31]
	v_mfma_f32_16x16x32_bf16 v[16:19], v[32:35], v[112:115], v[116:119]
	v_mov_b32_e32 v114, 0
	v_mov_b32_e32 v113, 0
	v_mov_b32_e32 v112, 0
	v_mfma_f32_16x16x32_bf16 v[20:23], v[32:35], v[120:123], v[124:127]
	v_mov_b32_e32 v118, 0
	v_mov_b32_e32 v119, 0
	v_mov_b32_e32 v117, 0
	v_mfma_f32_16x16x32_bf16 v[24:27], v[32:35], v[128:131], v[132:135]
	v_mov_b32_e32 v116, 0
	v_mov_b32_e32 v115, 0
	v_mfma_f32_16x16x32_bf16 v[28:31], v[32:35], v[136:139], v[140:143]
	v_mfma_f32_16x16x32_bf16 v[44:47], v[32:35], v[44:47], v[48:51]
	v_mfma_f32_16x16x32_bf16 v[48:51], v[32:35], v[52:55], v[56:59]
	v_max_f32_e32 v52, v4, v4
	v_max_f32_e32 v53, v0, v0
	v_max_f32_e32 v54, v5, v5
	v_max_f32_e32 v55, v1, v1
	v_max_f32_e32 v56, v6, v6
	v_max_f32_e32 v57, v2, v2
	v_max_f32_e32 v58, v7, v7
	v_max_f32_e32 v59, v3, v3
	v_mfma_f32_16x16x32_bf16 v[68:71], v[32:35], v[144:147], v[148:151]
	v_max_f32_e32 v52, v53, v52
	v_max_f32_e32 v53, v55, v54
	v_max_f32_e32 v54, v57, v56
	v_mfma_f32_16x16x32_bf16 v[72:75], v[32:35], v[72:75], v[92:95]
	v_max_f32_e32 v55, v59, v58
	v_max3_f32 v52, v52, v8, v12
	v_max3_f32 v53, v53, v9, v13
	v_mfma_f32_16x16x32_bf16 v[76:79], v[32:35], v[76:79], v[88:91]
	v_max3_f32 v54, v54, v10, v14
	v_max3_f32 v55, v55, v11, v15
	v_max3_f32 v52, v52, v16, v20
	v_mfma_f32_16x16x32_bf16 v[80:83], v[32:35], v[80:83], v[84:87]
	v_max3_f32 v53, v53, v17, v21
	v_max3_f32 v54, v54, v18, v22
	v_max3_f32 v55, v55, v19, v23
	v_mfma_f32_16x16x32_bf16 v[40:43], v[32:35], v[36:39], v[40:43]
	v_max3_f32 v52, v52, v24, v28
	v_max3_f32 v53, v53, v25, v29
	v_max3_f32 v54, v54, v26, v30
	s_waitcnt lgkmcnt(0)
	v_mfma_f32_16x16x32_bf16 v[32:35], v[32:35], v[60:63], v[64:67]
	v_max3_f32 v55, v55, v27, v31
	v_max3_f32 v52, v52, v68, v72
	v_max3_f32 v53, v53, v69, v73
	v_max3_f32 v54, v54, v70, v74
	v_max3_f32 v55, v55, v71, v75
	v_max3_f32 v52, v52, v76, v80
	v_max3_f32 v53, v53, v77, v81
	v_max3_f32 v54, v54, v78, v82
	v_max3_f32 v55, v55, v79, v83
	v_max3_f32 v52, v52, v40, v44
	v_max3_f32 v53, v53, v41, v45
	v_max3_f32 v54, v54, v42, v46
	v_max3_f32 v55, v55, v43, v47
	v_mov_b32_e32 v88, 0
	v_max3_f32 v52, v52, v48, v32
	v_max3_f32 v53, v53, v49, v33
	v_max3_f32 v54, v54, v50, v34
	v_max3_f32 v55, v55, v51, v35
	v_mov_b32_dpp v114, v52 row_ror:8 row_mask:0xf bank_mask:0xf
	v_mov_b32_dpp v118, v53 row_ror:8 row_mask:0xf bank_mask:0xf
	v_mov_b32_dpp v119, v54 row_ror:8 row_mask:0xf bank_mask:0xf
	v_mov_b32_dpp v88, v55 row_ror:8 row_mask:0xf bank_mask:0xf
	v_max_f32_e32 v56, v114, v114
	v_max_f32_e32 v57, v118, v118
	v_max_f32_e32 v58, v119, v119
	v_max_f32_e32 v59, v88, v88
	v_mov_b32_e32 v92, 0
	v_mov_b32_e32 v89, 0
	v_max_f32_e32 v52, v52, v56
	v_max_f32_e32 v53, v53, v57
	v_max_f32_e32 v54, v54, v58
	v_max_f32_e32 v55, v55, v59
	v_mov_b32_dpp v113, v52 row_ror:4 row_mask:0xf bank_mask:0xf
	v_mov_b32_dpp v117, v53 row_ror:4 row_mask:0xf bank_mask:0xf
	v_mov_b32_dpp v92, v54 row_ror:4 row_mask:0xf bank_mask:0xf
	v_mov_b32_dpp v89, v55 row_ror:4 row_mask:0xf bank_mask:0xf
	v_max_f32_e32 v56, v113, v113
	v_max_f32_e32 v57, v117, v117
	v_max_f32_e32 v58, v92, v92
	v_max_f32_e32 v59, v89, v89
	v_mov_b32_e32 v93, 0
	v_mov_b32_e32 v90, 0
	v_max_f32_e32 v52, v52, v56
	v_max_f32_e32 v53, v53, v57
	v_max_f32_e32 v54, v54, v58
	v_max_f32_e32 v55, v55, v59
	v_mov_b32_dpp v112, v52 row_ror:2 row_mask:0xf bank_mask:0xf
	v_mov_b32_dpp v116, v53 row_ror:2 row_mask:0xf bank_mask:0xf
	v_mov_b32_dpp v93, v54 row_ror:2 row_mask:0xf bank_mask:0xf
	v_mov_b32_dpp v90, v55 row_ror:2 row_mask:0xf bank_mask:0xf
	v_max_f32_e32 v56, v112, v112
	v_max_f32_e32 v57, v116, v116
	v_max_f32_e32 v58, v93, v93
	v_max_f32_e32 v59, v90, v90
	v_mov_b32_e32 v94, 0
	v_mov_b32_e32 v86, 0
	v_max_f32_e32 v52, v52, v56
	v_max_f32_e32 v53, v53, v57
	v_max_f32_e32 v54, v54, v58
	v_max_f32_e32 v55, v55, v59
	v_mov_b32_dpp v111, v52 row_ror:1 row_mask:0xf bank_mask:0xf
	v_mov_b32_dpp v115, v53 row_ror:1 row_mask:0xf bank_mask:0xf
	v_mov_b32_dpp v94, v54 row_ror:1 row_mask:0xf bank_mask:0xf
	v_mov_b32_dpp v86, v55 row_ror:1 row_mask:0xf bank_mask:0xf
	v_max_f32_e32 v56, v111, v111
	v_max_f32_e32 v57, v115, v115
	v_max_f32_e32 v58, v94, v94
	v_max_f32_e32 v59, v86, v86
	v_max_f32_e32 v52, v52, v56
	v_max_f32_e32 v53, v53, v57
	v_max_f32_e32 v54, v54, v58
	v_max_f32_e32 v55, v55, v59
	v_sub_f32_e32 v0, v0, v52
	v_sub_f32_e32 v4, v4, v52
	v_sub_f32_e32 v8, v8, v52
	v_sub_f32_e32 v12, v12, v52
	v_sub_f32_e32 v16, v16, v52
	v_sub_f32_e32 v20, v20, v52
	v_sub_f32_e32 v24, v24, v52
	v_sub_f32_e32 v28, v28, v52
	v_sub_f32_e32 v56, v68, v52
	v_sub_f32_e32 v57, v72, v52
	v_sub_f32_e32 v58, v76, v52
	v_sub_f32_e32 v59, v80, v52
	v_sub_f32_e32 v40, v40, v52
	v_sub_f32_e32 v44, v44, v52
	v_sub_f32_e32 v48, v48, v52
	v_sub_f32_e32 v32, v32, v52
	v_sub_f32_e32 v1, v1, v53
	v_sub_f32_e32 v5, v5, v53
	v_sub_f32_e32 v9, v9, v53
	v_sub_f32_e32 v13, v13, v53
	v_sub_f32_e32 v17, v17, v53
	v_sub_f32_e32 v21, v21, v53
	v_sub_f32_e32 v29, v29, v53
	v_sub_f32_e32 v52, v69, v53
	v_sub_f32_e32 v60, v73, v53
	v_sub_f32_e32 v61, v77, v53
	v_sub_f32_e32 v62, v81, v53
	v_sub_f32_e32 v41, v41, v53
	v_sub_f32_e32 v45, v45, v53
	v_sub_f32_e32 v33, v33, v53
	v_sub_f32_e32 v2, v2, v54
	v_sub_f32_e32 v10, v10, v54
	v_sub_f32_e32 v18, v18, v54
	v_sub_f32_e32 v22, v22, v54
	v_sub_f32_e32 v63, v74, v54
	v_sub_f32_e32 v64, v78, v54
	v_sub_f32_e32 v65, v82, v54
	v_sub_f32_e32 v3, v3, v55
	v_sub_f32_e32 v11, v11, v55
	v_sub_f32_e32 v25, v25, v53
	v_sub_f32_e32 v49, v49, v53
	v_sub_f32_e32 v6, v6, v54
	v_sub_f32_e32 v14, v14, v54
	v_sub_f32_e32 v26, v26, v54
	v_sub_f32_e32 v30, v30, v54
	v_sub_f32_e32 v53, v70, v54
	v_sub_f32_e32 v42, v42, v54
	v_sub_f32_e32 v46, v46, v54
	v_sub_f32_e32 v50, v50, v54
	v_sub_f32_e32 v34, v34, v54
	v_sub_f32_e32 v7, v7, v55
	v_sub_f32_e32 v15, v15, v55
	v_sub_f32_e32 v19, v19, v55
	v_sub_f32_e32 v23, v23, v55
	v_sub_f32_e32 v27, v27, v55
	v_sub_f32_e32 v31, v31, v55
	v_sub_f32_e32 v54, v71, v55
	v_sub_f32_e32 v66, v75, v55
	v_sub_f32_e32 v67, v79, v55
	v_sub_f32_e32 v68, v83, v55
	v_sub_f32_e32 v43, v43, v55
	v_sub_f32_e32 v47, v47, v55
	v_sub_f32_e32 v51, v51, v55
	v_sub_f32_e32 v35, v35, v55
	v_mul_f32_e32 v0, 0x3fb8aa3b, v0
	v_mul_f32_e32 v4, 0x3fb8aa3b, v4
	v_mul_f32_e32 v8, 0x3fb8aa3b, v8
	v_mul_f32_e32 v12, 0x3fb8aa3b, v12
	v_mul_f32_e32 v16, 0x3fb8aa3b, v16
	v_mul_f32_e32 v20, 0x3fb8aa3b, v20
	v_mul_f32_e32 v24, 0x3fb8aa3b, v24
	v_mul_f32_e32 v28, 0x3fb8aa3b, v28
	v_mul_f32_e32 v55, 0x3fb8aa3b, v56
	v_mul_f32_e32 v56, 0x3fb8aa3b, v57
	v_mul_f32_e32 v57, 0x3fb8aa3b, v58
	v_mul_f32_e32 v58, 0x3fb8aa3b, v59
	v_mul_f32_e32 v40, 0x3fb8aa3b, v40
	v_mul_f32_e32 v44, 0x3fb8aa3b, v44
	v_mul_f32_e32 v48, 0x3fb8aa3b, v48
	v_mul_f32_e32 v32, 0x3fb8aa3b, v32
	v_mul_f32_e32 v1, 0x3fb8aa3b, v1
	v_mul_f32_e32 v5, 0x3fb8aa3b, v5
	v_mul_f32_e32 v9, 0x3fb8aa3b, v9
	v_mul_f32_e32 v13, 0x3fb8aa3b, v13
	v_mul_f32_e32 v17, 0x3fb8aa3b, v17
	v_mul_f32_e32 v21, 0x3fb8aa3b, v21
	v_mul_f32_e32 v29, 0x3fb8aa3b, v29
	v_mul_f32_e32 v52, 0x3fb8aa3b, v52
	v_mul_f32_e32 v59, 0x3fb8aa3b, v60
	v_mul_f32_e32 v60, 0x3fb8aa3b, v61
	v_mul_f32_e32 v61, 0x3fb8aa3b, v62
	v_mul_f32_e32 v41, 0x3fb8aa3b, v41
	v_mul_f32_e32 v45, 0x3fb8aa3b, v45
	v_mul_f32_e32 v33, 0x3fb8aa3b, v33
	v_mul_f32_e32 v2, 0x3fb8aa3b, v2
	v_mul_f32_e32 v10, 0x3fb8aa3b, v10
	v_mul_f32_e32 v18, 0x3fb8aa3b, v18
	v_mul_f32_e32 v22, 0x3fb8aa3b, v22
	v_mul_f32_e32 v62, 0x3fb8aa3b, v63
	v_mul_f32_e32 v63, 0x3fb8aa3b, v64
	v_mul_f32_e32 v64, 0x3fb8aa3b, v65
	v_mul_f32_e32 v3, 0x3fb8aa3b, v3
	v_mul_f32_e32 v11, 0x3fb8aa3b, v11
	v_mul_f32_e32 v25, 0x3fb8aa3b, v25
	v_mul_f32_e32 v49, 0x3fb8aa3b, v49
	v_mul_f32_e32 v6, 0x3fb8aa3b, v6
	v_mul_f32_e32 v14, 0x3fb8aa3b, v14
	v_mul_f32_e32 v26, 0x3fb8aa3b, v26
	v_mul_f32_e32 v30, 0x3fb8aa3b, v30
	v_mul_f32_e32 v53, 0x3fb8aa3b, v53
	v_mul_f32_e32 v42, 0x3fb8aa3b, v42
	v_mul_f32_e32 v46, 0x3fb8aa3b, v46
	v_mul_f32_e32 v50, 0x3fb8aa3b, v50
	v_mul_f32_e32 v34, 0x3fb8aa3b, v34
	v_mul_f32_e32 v7, 0x3fb8aa3b, v7
	v_mul_f32_e32 v15, 0x3fb8aa3b, v15
	v_mul_f32_e32 v19, 0x3fb8aa3b, v19
	v_mul_f32_e32 v23, 0x3fb8aa3b, v23
	v_mul_f32_e32 v27, 0x3fb8aa3b, v27
	v_mul_f32_e32 v31, 0x3fb8aa3b, v31
	v_mul_f32_e32 v54, 0x3fb8aa3b, v54
	v_mul_f32_e32 v65, 0x3fb8aa3b, v66
	v_mul_f32_e32 v66, 0x3fb8aa3b, v67
	v_mul_f32_e32 v67, 0x3fb8aa3b, v68
	v_mul_f32_e32 v43, 0x3fb8aa3b, v43
	v_mul_f32_e32 v47, 0x3fb8aa3b, v47
	v_mul_f32_e32 v51, 0x3fb8aa3b, v51
	v_mul_f32_e32 v35, 0x3fb8aa3b, v35
	v_exp_f32_e32 v0, v0
	v_exp_f32_e32 v4, v4
	v_exp_f32_e32 v8, v8
	v_exp_f32_e32 v12, v12
	v_exp_f32_e32 v111, v16
	v_exp_f32_e32 v156, v20
	v_exp_f32_e32 v157, v24
	v_exp_f32_e32 v158, v28
	v_exp_f32_e32 v159, v55
	v_exp_f32_e32 v160, v56
	v_exp_f32_e32 v161, v57
	v_exp_f32_e32 v162, v58
	v_exp_f32_e32 v163, v40
	v_exp_f32_e32 v164, v44
	v_exp_f32_e32 v165, v48
	v_exp_f32_e32 v166, v32
	v_exp_f32_e32 v1, v1
	v_exp_f32_e32 v5, v5
	v_exp_f32_e32 v9, v9
	v_exp_f32_e32 v13, v13
	v_exp_f32_e32 v167, v17
	v_exp_f32_e32 v168, v21
	v_exp_f32_e32 v170, v29
	v_exp_f32_e32 v171, v52
	v_exp_f32_e32 v172, v59
	v_exp_f32_e32 v174, v61
	v_exp_f32_e32 v175, v41
	v_exp_f32_e32 v177, v45
	v_exp_f32_e32 v181, v33
	v_exp_f32_e32 v2, v2
	v_exp_f32_e32 v10, v10
	v_exp_f32_e32 v182, v18
	v_exp_f32_e32 v183, v22
	v_exp_f32_e32 v188, v63
	v_exp_f32_e32 v189, v64
	v_exp_f32_e32 v3, v3
	v_exp_f32_e32 v11, v11
	v_lshl_add_u64 v[84:85], v[100:101], 0, v[102:103]
	v_exp_f32_e32 v169, v25
	v_exp_f32_e32 v173, v60
	v_exp_f32_e32 v180, v49
	v_exp_f32_e32 v6, v6
	v_exp_f32_e32 v14, v14
	v_exp_f32_e32 v184, v26
	v_exp_f32_e32 v185, v30
	v_exp_f32_e32 v186, v53
	v_exp_f32_e32 v187, v62
	v_exp_f32_e32 v190, v42
	v_exp_f32_e32 v191, v46
	v_exp_f32_e32 v192, v50
	v_exp_f32_e32 v193, v34
	v_exp_f32_e32 v7, v7
	v_exp_f32_e32 v15, v15
	v_exp_f32_e32 v194, v19
	v_exp_f32_e32 v195, v23
	v_exp_f32_e32 v196, v27
	v_exp_f32_e32 v197, v31
	v_exp_f32_e32 v198, v54
	v_exp_f32_e32 v199, v65
	v_exp_f32_e32 v200, v66
	v_exp_f32_e32 v201, v67
	v_exp_f32_e32 v202, v43
	v_exp_f32_e32 v203, v47
	v_exp_f32_e32 v204, v51
	v_exp_f32_e32 v205, v35
	v_add_co_u32_e32 v36, vcc, s8, v84
	v_add_f32_e32 v16, 0, v0
	s_nop 0
	v_addc_co_u32_e32 v37, vcc, 0, v85, vcc
	v_add_co_u32_e32 v38, vcc, s10, v84
	v_bfe_u32 v17, v0, 16, 1
	v_bfe_u32 v18, v4, 16, 1
	v_bfe_u32 v19, v8, 16, 1
	v_bfe_u32 v20, v12, 16, 1
	v_bfe_u32 v21, v111, 16, 1
	v_bfe_u32 v22, v156, 16, 1
	v_bfe_u32 v23, v157, 16, 1
	v_bfe_u32 v24, v158, 16, 1
	v_bfe_u32 v25, v159, 16, 1
	v_bfe_u32 v26, v160, 16, 1
	v_bfe_u32 v27, v161, 16, 1
	v_bfe_u32 v28, v162, 16, 1
	v_bfe_u32 v29, v163, 16, 1
	v_bfe_u32 v30, v164, 16, 1
	v_bfe_u32 v31, v165, 16, 1
	v_bfe_u32 v32, v166, 16, 1
	v_add_f32_e32 v33, 0, v1
	v_bfe_u32 v34, v1, 16, 1
	v_bfe_u32 v35, v5, 16, 1
	v_bfe_u32 v40, v9, 16, 1
	v_bfe_u32 v41, v13, 16, 1
	v_bfe_u32 v42, v167, 16, 1
	v_bfe_u32 v43, v168, 16, 1
	v_bfe_u32 v45, v170, 16, 1
	v_bfe_u32 v46, v171, 16, 1
	v_bfe_u32 v47, v172, 16, 1
	v_bfe_u32 v49, v174, 16, 1
	v_bfe_u32 v50, v175, 16, 1
	v_bfe_u32 v51, v177, 16, 1
	v_bfe_u32 v53, v181, 16, 1
	v_add_f32_e32 v54, 0, v2
	v_bfe_u32 v55, v2, 16, 1
	v_bfe_u32 v57, v10, 16, 1
	v_bfe_u32 v59, v182, 16, 1
	v_bfe_u32 v60, v183, 16, 1
	v_bfe_u32 v65, v188, 16, 1
	v_bfe_u32 v66, v189, 16, 1
	v_add_f32_e32 v71, 0, v3
	v_bfe_u32 v72, v3, 16, 1
	v_bfe_u32 v74, v11, 16, 1
	v_addc_co_u32_e32 v39, vcc, 0, v85, vcc
	v_bfe_u32 v44, v169, 16, 1
	v_bfe_u32 v48, v173, 16, 1
	v_bfe_u32 v52, v180, 16, 1
	v_bfe_u32 v56, v6, 16, 1
	v_bfe_u32 v58, v14, 16, 1
	v_bfe_u32 v61, v184, 16, 1
	v_bfe_u32 v62, v185, 16, 1
	v_bfe_u32 v63, v186, 16, 1
	v_bfe_u32 v64, v187, 16, 1
	v_bfe_u32 v67, v190, 16, 1
	v_bfe_u32 v68, v191, 16, 1
	v_bfe_u32 v69, v192, 16, 1
	v_bfe_u32 v70, v193, 16, 1
	v_bfe_u32 v73, v7, 16, 1
	v_bfe_u32 v75, v15, 16, 1
	v_bfe_u32 v76, v194, 16, 1
	v_bfe_u32 v77, v195, 16, 1
	v_bfe_u32 v78, v196, 16, 1
	v_bfe_u32 v79, v197, 16, 1
	v_bfe_u32 v80, v198, 16, 1
	v_bfe_u32 v81, v199, 16, 1
	v_bfe_u32 v82, v200, 16, 1
	v_bfe_u32 v83, v201, 16, 1
	v_bfe_u32 v84, v202, 16, 1
	v_bfe_u32 v85, v203, 16, 1
	v_bfe_u32 v86, v204, 16, 1
	v_bfe_u32 v87, v205, 16, 1
	v_add3_u32 v0, v0, v17, s9
	v_add_f32_e32 v16, v4, v16
	v_add3_u32 v4, v4, v18, s9
	v_add3_u32 v17, v8, v19, s9
	v_add3_u32 v18, v12, v20, s9
	v_add3_u32 v19, v111, v21, s9
	v_add3_u32 v20, v156, v22, s9
	v_add3_u32 v21, v157, v23, s9
	v_add3_u32 v22, v158, v24, s9
	v_add3_u32 v23, v159, v25, s9
	v_add3_u32 v24, v160, v26, s9
	v_add3_u32 v25, v161, v27, s9
	v_add3_u32 v26, v162, v28, s9
	v_add3_u32 v27, v163, v29, s9
	v_add3_u32 v28, v164, v30, s9
	v_add3_u32 v29, v165, v31, s9
	v_add3_u32 v30, v166, v32, s9
	v_add3_u32 v1, v1, v34, s9
	v_add_f32_e32 v31, v5, v33
	v_add3_u32 v5, v5, v35, s9
	v_add3_u32 v32, v9, v40, s9
	v_add3_u32 v33, v13, v41, s9
	v_add3_u32 v34, v167, v42, s9
	v_add3_u32 v35, v168, v43, s9
	v_add3_u32 v41, v170, v45, s9
	v_add3_u32 v42, v171, v46, s9
	v_add3_u32 v43, v172, v47, s9
	v_add3_u32 v45, v174, v49, s9
	v_add3_u32 v46, v175, v50, s9
	v_add3_u32 v47, v177, v51, s9
	v_add3_u32 v49, v181, v53, s9
	v_add3_u32 v2, v2, v55, s9
	v_add_f32_e32 v50, v6, v54
	v_add3_u32 v51, v10, v57, s9
	v_add3_u32 v53, v182, v59, s9
	v_add3_u32 v54, v183, v60, s9
	v_add3_u32 v59, v188, v65, s9
	v_add3_u32 v60, v189, v66, s9
	v_add3_u32 v3, v3, v72, s9
	v_add_f32_e32 v65, v7, v71
	v_add3_u32 v66, v11, v74, s9
	v_add3_u32 v40, v169, v44, s9
	v_add3_u32 v44, v173, v48, s9
	v_add3_u32 v48, v180, v52, s9
	v_add3_u32 v6, v6, v56, s9
	v_add3_u32 v52, v14, v58, s9
	v_add3_u32 v55, v184, v61, s9
	v_add3_u32 v56, v185, v62, s9
	v_add3_u32 v57, v186, v63, s9
	v_add3_u32 v58, v187, v64, s9
	v_add3_u32 v61, v190, v67, s9
	v_add3_u32 v62, v191, v68, s9
	v_add3_u32 v63, v192, v69, s9
	v_add3_u32 v64, v193, v70, s9
	v_add3_u32 v7, v7, v73, s9
	v_add3_u32 v67, v15, v75, s9
	v_add3_u32 v68, v194, v76, s9
	v_add3_u32 v69, v195, v77, s9
	v_add3_u32 v70, v196, v78, s9
	v_add3_u32 v71, v197, v79, s9
	v_add3_u32 v72, v198, v80, s9
	v_add3_u32 v73, v199, v81, s9
	v_add3_u32 v74, v200, v82, s9
	v_add3_u32 v75, v201, v83, s9
	v_add3_u32 v76, v202, v84, s9
	v_add3_u32 v77, v203, v85, s9
	v_add3_u32 v78, v204, v86, s9
	v_add3_u32 v79, v205, v87, s9
	ds_write_b16_d16_hi v109, v0
	ds_write_b16_d16_hi v109, v4 offset:32
	v_add_f32_e32 v0, v8, v16
	ds_write_b16_d16_hi v109, v17 offset:64
	ds_write_b16_d16_hi v109, v18 offset:96
	ds_write_b16_d16_hi v109, v19 offset:128
	ds_write_b16_d16_hi v109, v20 offset:160
	ds_write_b16_d16_hi v109, v21 offset:192
	ds_write_b16_d16_hi v109, v22 offset:224
	ds_write_b16_d16_hi v109, v23 offset:256
	ds_write_b16_d16_hi v109, v24 offset:288
	ds_write_b16_d16_hi v109, v25 offset:320
	ds_write_b16_d16_hi v109, v26 offset:352
	ds_write_b16_d16_hi v109, v27 offset:384
	ds_write_b16_d16_hi v109, v28 offset:416
	ds_write_b16_d16_hi v109, v29 offset:448
	ds_write_b16_d16_hi v109, v30 offset:480
	ds_write_b16_d16_hi v109, v1 offset:528
	ds_write_b16_d16_hi v109, v5 offset:560
	v_add_f32_e32 v1, v9, v31
	ds_write_b16_d16_hi v109, v32 offset:592
	ds_write_b16_d16_hi v109, v33 offset:624
	ds_write_b16_d16_hi v109, v34 offset:656
	ds_write_b16_d16_hi v109, v35 offset:688
	ds_write_b16_d16_hi v109, v40 offset:720
	ds_write_b16_d16_hi v109, v41 offset:752
	ds_write_b16_d16_hi v109, v42 offset:784
	ds_write_b16_d16_hi v109, v43 offset:816
	ds_write_b16_d16_hi v109, v44 offset:848
	ds_write_b16_d16_hi v109, v45 offset:880
	ds_write_b16_d16_hi v109, v46 offset:912
	ds_write_b16_d16_hi v109, v47 offset:944
	ds_write_b16_d16_hi v109, v48 offset:976
	ds_write_b16_d16_hi v109, v49 offset:1008
	ds_write_b16_d16_hi v109, v2 offset:1056
	ds_write_b16_d16_hi v109, v6 offset:1088
	v_add_f32_e32 v2, v10, v50
	ds_write_b16_d16_hi v109, v51 offset:1120
	ds_write_b16_d16_hi v109, v52 offset:1152
	ds_write_b16_d16_hi v109, v53 offset:1184
	ds_write_b16_d16_hi v109, v54 offset:1216
	ds_write_b16_d16_hi v109, v55 offset:1248
	ds_write_b16_d16_hi v109, v56 offset:1280
	ds_write_b16_d16_hi v109, v57 offset:1312
	ds_write_b16_d16_hi v109, v58 offset:1344
	ds_write_b16_d16_hi v109, v59 offset:1376
	ds_write_b16_d16_hi v109, v60 offset:1408
	ds_write_b16_d16_hi v109, v61 offset:1440
	ds_write_b16_d16_hi v109, v62 offset:1472
	ds_write_b16_d16_hi v109, v63 offset:1504
	ds_write_b16_d16_hi v109, v64 offset:1536
	ds_write_b16_d16_hi v109, v3 offset:1584
	ds_write_b16_d16_hi v109, v7 offset:1616
	v_add_f32_e32 v3, v11, v65
	ds_write_b16_d16_hi v109, v66 offset:1648
	ds_write_b16_d16_hi v109, v67 offset:1680
	ds_write_b16_d16_hi v109, v68 offset:1712
	ds_write_b16_d16_hi v109, v69 offset:1744
	ds_write_b16_d16_hi v109, v70 offset:1776
	ds_write_b16_d16_hi v109, v71 offset:1808
	ds_write_b16_d16_hi v109, v72 offset:1840
	ds_write_b16_d16_hi v109, v73 offset:1872
	ds_write_b16_d16_hi v109, v74 offset:1904
	ds_write_b16_d16_hi v109, v75 offset:1936
	ds_write_b16_d16_hi v109, v76 offset:1968
	ds_write_b16_d16_hi v109, v77 offset:2000
	ds_write_b16_d16_hi v109, v78 offset:2032
	ds_write_b16_d16_hi v109, v79 offset:2064
	v_add_f32_e32 v206, v12, v0
	v_add_f32_e32 v207, v13, v1
	v_add_f32_e32 v208, v14, v2
	v_add_f32_e32 v209, v15, v3
	ds_read_b128 v[0:3], v104
	ds_read_b128 v[4:7], v104 offset:64
	ds_read_b128 v[8:11], v97 offset:36864
	ds_read_b128 v[12:15], v97 offset:36928
	ds_read_b128 v[16:19], v110 offset:36864
	ds_read_b128 v[20:23], v110 offset:36928
	ds_read_b128 v[24:27], v110 offset:45312
	ds_read_b128 v[28:31], v110 offset:45376
	ds_read_b128 v[32:35], v110 offset:53760
	ds_read_b128 v[40:43], v110 offset:53824
	ds_read_b128 v[44:47], v110 offset:36992
	ds_read_b128 v[48:51], v110 offset:53888
	ds_read_b128 v[52:55], v104 offset:128
	ds_read_b128 v[56:59], v104 offset:192
	ds_read_b128 v[60:63], v97 offset:36992
	ds_read_b128 v[64:67], v97 offset:37056
	s_waitcnt lgkmcnt(13)
	v_mfma_f32_16x16x32_bf16 v[8:11], v[0:3], v[8:11], 0
	ds_read_b128 v[68:71], v110 offset:37056
	ds_read_b128 v[72:75], v110 offset:45440
	ds_read_b128 v[76:79], v110 offset:45504
	ds_read_b128 v[80:83], v110 offset:53952
	ds_read_b128 v[84:87], v104 offset:256
	ds_read_b128 v[88:91], v110 offset:37120
	ds_read_b128 v[92:95], v104 offset:320
	ds_read_b128 v[112:115], v97 offset:37120
	ds_read_b128 v[116:119], v97 offset:37184
	s_waitcnt lgkmcnt(14)
	v_mfma_f32_16x16x32_bf16 v[16:19], v[0:3], v[16:19], 0
	v_cmp_lt_i32_e32 vcc, s11, v96
	v_lshl_add_u64 v[100:101], v[100:101], 0, s[2:3]
	s_or_b64 s[6:7], vcc, s[6:7]
	v_mfma_f32_16x16x32_bf16 v[24:27], v[0:3], v[24:27], 0
	v_mfma_f32_16x16x32_bf16 v[0:3], v[0:3], v[32:35], 0
	ds_read_b128 v[32:35], v110 offset:37184
	ds_read_b128 v[120:123], v110 offset:45568
	ds_read_b128 v[124:127], v110 offset:45632
	v_mfma_f32_16x16x32_bf16 v[8:11], v[4:7], v[12:15], v[8:11]
	ds_read_b128 v[12:15], v110 offset:54016
	ds_read_b128 v[128:131], v110 offset:54080
	ds_read_b128 v[132:135], v97 offset:37248
	v_mfma_f32_16x16x32_bf16 v[16:19], v[4:7], v[20:23], v[16:19]
	ds_read_b128 v[20:23], v110 offset:45696
	ds_read_b128 v[136:139], v104 offset:384
	ds_read_b128 v[140:143], v104 offset:448
	v_mfma_f32_16x16x32_bf16 v[24:27], v[4:7], v[28:31], v[24:27]
	ds_read_b128 v[28:31], v97 offset:37312
	ds_read_b128 v[144:147], v110 offset:37248
	ds_read_b128 v[148:151], v110 offset:37312
	v_mfma_f32_16x16x32_bf16 v[0:3], v[4:7], v[40:43], v[0:3]
	ds_read_b128 v[4:7], v110 offset:45760
	ds_read_b128 v[40:43], v110 offset:54144
	ds_read_b128 v[152:155], v110 offset:54208
	s_waitcnt vmcnt(0)
	s_waitcnt lgkmcnt(14)
	v_mfma_f32_16x16x32_bf16 v[8:11], v[52:55], v[60:63], v[8:11]
	v_add_f32_e32 v60, v111, v206
	v_add_f32_e32 v61, v167, v207
	v_mfma_f32_16x16x32_bf16 v[16:19], v[52:55], v[44:47], v[16:19]
	v_add_f32_e32 v44, v182, v208
	v_add_f32_e32 v45, v194, v209
	v_add_f32_e32 v46, v156, v60
	v_mfma_f32_16x16x32_bf16 v[24:27], v[52:55], v[72:75], v[24:27]
	v_add_f32_e32 v47, v168, v61
	v_add_f32_e32 v44, v183, v44
	v_add_f32_e32 v45, v195, v45
	v_mfma_f32_16x16x32_bf16 v[0:3], v[52:55], v[48:51], v[0:3]
	v_add_f32_e32 v46, v157, v46
	v_add_f32_e32 v47, v169, v47
	v_add_f32_e32 v44, v184, v44
	v_mfma_f32_16x16x32_bf16 v[8:11], v[56:59], v[64:67], v[8:11]
	v_add_f32_e32 v45, v196, v45
	v_add_f32_e32 v46, v158, v46
	v_add_f32_e32 v47, v170, v47
	v_mfma_f32_16x16x32_bf16 v[16:19], v[56:59], v[68:71], v[16:19]
	v_add_f32_e32 v44, v185, v44
	v_add_f32_e32 v45, v197, v45
	v_add_f32_e32 v46, v159, v46
	v_mfma_f32_16x16x32_bf16 v[24:27], v[56:59], v[76:79], v[24:27]
	v_add_f32_e32 v47, v171, v47
	v_add_f32_e32 v44, v186, v44
	v_add_f32_e32 v45, v198, v45
	v_mfma_f32_16x16x32_bf16 v[0:3], v[56:59], v[80:83], v[0:3]
	v_add_f32_e32 v46, v160, v46
	v_add_f32_e32 v47, v172, v47
	v_add_f32_e32 v44, v187, v44
	v_mfma_f32_16x16x32_bf16 v[8:11], v[84:87], v[112:115], v[8:11]
	v_add_f32_e32 v45, v199, v45
	v_add_f32_e32 v46, v161, v46
	v_add_f32_e32 v47, v173, v47
	v_mfma_f32_16x16x32_bf16 v[16:19], v[84:87], v[88:91], v[16:19]
	v_add_f32_e32 v44, v188, v44
	v_add_f32_e32 v45, v200, v45
	v_add_f32_e32 v46, v162, v46
	s_waitcnt lgkmcnt(13)
	v_mfma_f32_16x16x32_bf16 v[24:27], v[84:87], v[120:123], v[24:27]
	v_add_f32_e32 v47, v174, v47
	v_add_f32_e32 v44, v189, v44
	v_add_f32_e32 v45, v201, v45
	s_waitcnt lgkmcnt(11)
	v_mfma_f32_16x16x32_bf16 v[0:3], v[84:87], v[12:15], v[0:3]
	v_add_f32_e32 v12, v163, v46
	v_add_f32_e32 v13, v175, v47
	v_add_f32_e32 v44, v190, v44
	v_mfma_f32_16x16x32_bf16 v[8:11], v[92:95], v[116:119], v[8:11]
	v_add_f32_e32 v45, v202, v45
	v_add_f32_e32 v46, v164, v12
	v_add_f32_e32 v47, v177, v13
	v_mfma_f32_16x16x32_bf16 v[12:15], v[92:95], v[32:35], v[16:19]
	v_add_f32_e32 v32, v191, v44
	v_add_f32_e32 v33, v203, v45
	v_add_f32_e32 v34, v165, v46
	v_mfma_f32_16x16x32_bf16 v[16:19], v[92:95], v[124:127], v[24:27]
	s_waitcnt lgkmcnt(10)
	v_mfma_f32_16x16x32_bf16 v[0:3], v[92:95], v[128:131], v[0:3]
	s_nop 0
	v_add_f32_e32 v24, v180, v47
	v_add_f32_e32 v25, v192, v32
	v_add_f32_e32 v26, v204, v33
	v_add_f32_e32 v27, v166, v34
	v_add_f32_e32 v24, v181, v24
	v_add_f32_e32 v25, v193, v25
	s_waitcnt lgkmcnt(7)
	v_mfma_f32_16x16x32_bf16 v[8:11], v[136:139], v[132:135], v[8:11]
	v_add_f32_e32 v26, v205, v26
	v_add_f32_dpp v27, v27, v27 row_ror:8 row_mask:0xf bank_mask:0xf bound_ctrl:1
	v_add_f32_dpp v24, v24, v24 row_ror:8 row_mask:0xf bank_mask:0xf bound_ctrl:1
	s_waitcnt lgkmcnt(4)
	v_mfma_f32_16x16x32_bf16 v[12:15], v[136:139], v[144:147], v[12:15]
	v_add_f32_dpp v25, v25, v25 row_ror:8 row_mask:0xf bank_mask:0xf bound_ctrl:1
	v_add_f32_dpp v26, v26, v26 row_ror:8 row_mask:0xf bank_mask:0xf bound_ctrl:1
	v_add_f32_dpp v27, v27, v27 row_ror:4 row_mask:0xf bank_mask:0xf bound_ctrl:1
	v_mfma_f32_16x16x32_bf16 v[16:19], v[136:139], v[20:23], v[16:19]
	v_add_f32_dpp v20, v24, v24 row_ror:4 row_mask:0xf bank_mask:0xf bound_ctrl:1
	v_add_f32_dpp v21, v25, v25 row_ror:4 row_mask:0xf bank_mask:0xf bound_ctrl:1
	v_add_f32_dpp v22, v26, v26 row_ror:4 row_mask:0xf bank_mask:0xf bound_ctrl:1
	s_waitcnt lgkmcnt(1)
	v_mfma_f32_16x16x32_bf16 v[0:3], v[136:139], v[40:43], v[0:3]
	v_add_f32_dpp v23, v27, v27 row_ror:2 row_mask:0xf bank_mask:0xf bound_ctrl:1
	v_add_f32_dpp v20, v20, v20 row_ror:2 row_mask:0xf bank_mask:0xf bound_ctrl:1
	v_add_f32_dpp v21, v21, v21 row_ror:2 row_mask:0xf bank_mask:0xf bound_ctrl:1
	v_add_f32_dpp v22, v22, v22 row_ror:2 row_mask:0xf bank_mask:0xf bound_ctrl:1
	v_add_f32_dpp v23, v23, v23 row_ror:1 row_mask:0xf bank_mask:0xf bound_ctrl:1
	v_mfma_f32_16x16x32_bf16 v[8:11], v[140:143], v[28:31], v[8:11]
	v_add_f32_dpp v20, v20, v20 row_ror:1 row_mask:0xf bank_mask:0xf bound_ctrl:1
	v_add_f32_dpp v21, v21, v21 row_ror:1 row_mask:0xf bank_mask:0xf bound_ctrl:1
	v_add_f32_dpp v22, v22, v22 row_ror:1 row_mask:0xf bank_mask:0xf bound_ctrl:1
	v_rcp_f32_e32 v23, v23
	v_mfma_f32_16x16x32_bf16 v[12:15], v[140:143], v[148:151], v[12:15]
	s_nop 2
	v_mul_f32_e32 v8, v23, v8
	v_mfma_f32_16x16x32_bf16 v[4:7], v[140:143], v[4:7], v[16:19]
	s_nop 2
	v_rcp_f32_e32 v16, v20
	v_rcp_f32_e32 v17, v21
	v_rcp_f32_e32 v18, v22
	s_waitcnt lgkmcnt(0)
	v_mfma_f32_16x16x32_bf16 v[0:3], v[140:143], v[152:155], v[0:3]
	v_mul_f32_e32 v9, v16, v9
	v_mul_f32_e32 v10, v17, v10
	v_mul_f32_e32 v11, v18, v11
	v_mul_f32_e32 v12, v23, v12
	v_mul_f32_e32 v13, v16, v13
	v_mul_f32_e32 v14, v17, v14
	v_mul_f32_e32 v15, v18, v15
	v_mul_f32_e32 v4, v23, v4
	v_mul_f32_e32 v5, v16, v5
	v_mul_f32_e32 v6, v17, v6
	v_mul_f32_e32 v7, v18, v7
	v_mul_f32_e32 v0, v23, v0
	v_mul_f32_e32 v1, v16, v1
	v_mul_f32_e32 v2, v17, v2
	v_mul_f32_e32 v3, v18, v3
	v_bfe_u32 v16, v8, 16, 1
	v_bfe_u32 v17, v9, 16, 1
	v_bfe_u32 v18, v10, 16, 1
	v_bfe_u32 v19, v11, 16, 1
	v_bfe_u32 v20, v12, 16, 1
	v_bfe_u32 v21, v13, 16, 1
	v_bfe_u32 v22, v14, 16, 1
	v_bfe_u32 v23, v15, 16, 1
	v_bfe_u32 v24, v4, 16, 1
	v_bfe_u32 v25, v5, 16, 1
	v_bfe_u32 v26, v6, 16, 1
	v_bfe_u32 v27, v7, 16, 1
	v_bfe_u32 v28, v0, 16, 1
	v_bfe_u32 v29, v1, 16, 1
	v_bfe_u32 v30, v2, 16, 1
	v_bfe_u32 v31, v3, 16, 1
	v_add3_u32 v8, v8, v16, s9
	v_add3_u32 v9, v9, v17, s9
	v_add3_u32 v10, v10, v18, s9
	v_add3_u32 v11, v11, v19, s9
	v_add3_u32 v12, v12, v20, s9
	v_add3_u32 v13, v13, v21, s9
	v_add3_u32 v14, v14, v22, s9
	v_add3_u32 v15, v15, v23, s9
	v_add3_u32 v4, v4, v24, s9
	v_add3_u32 v5, v5, v25, s9
	v_add3_u32 v6, v6, v26, s9
	v_add3_u32 v7, v7, v27, s9
	v_add3_u32 v0, v0, v28, s9
	v_add3_u32 v1, v1, v29, s9
	v_add3_u32 v2, v2, v30, s9
	v_add3_u32 v3, v3, v31, s9
	s_mov_b32 s98, 0xaaaaaaaa
	s_mov_b32 s99, 0xaaaaaaaa
	v_mov_b32_e32 v240, 0x7060302
	v_and_b32_e32 v238, 1, v176
	v_mul_u32_u24_e32 v238, 0x7fe, v238
	v_mov_b32_e32 v239, 0
	v_lshl_add_u64 v[232:233], v[36:37], 0, v[238:239]
	v_mov_b32_dpp v236, v8 row_shl:1 row_mask:0xf bank_mask:0xf
	v_mov_b32_dpp v237, v9 row_shr:1 row_mask:0xf bank_mask:0xf
	v_perm_b32 v236, v236, v8, v240
	v_perm_b32 v237, v9, v237, v240
	v_cndmask_b32_e64 v236, v236, v237, s[98:99]
	global_store_dword v[232:233], v236, off offset:1536
	v_lshl_add_u64 v[234:235], v[38:39], 0, v[238:239]
	v_mov_b32_dpp v236, v10 row_shl:1 row_mask:0xf bank_mask:0xf
	v_mov_b32_dpp v237, v11 row_shr:1 row_mask:0xf bank_mask:0xf
	v_perm_b32 v236, v236, v10, v240
	v_perm_b32 v237, v11, v237, v240
	v_cndmask_b32_e64 v236, v236, v237, s[98:99]
	global_store_dword v[234:235], v236, off offset:1536
	v_mov_b32_dpp v236, v12 row_shl:1 row_mask:0xf bank_mask:0xf
	v_mov_b32_dpp v237, v13 row_shr:1 row_mask:0xf bank_mask:0xf
	v_perm_b32 v236, v236, v12, v240
	v_perm_b32 v237, v13, v237, v240
	v_cndmask_b32_e64 v236, v236, v237, s[98:99]
	global_store_dword v[232:233], v236, off offset:1568
	v_mov_b32_dpp v236, v14 row_shl:1 row_mask:0xf bank_mask:0xf
	v_mov_b32_dpp v237, v15 row_shr:1 row_mask:0xf bank_mask:0xf
	v_perm_b32 v236, v236, v14, v240
	v_perm_b32 v237, v15, v237, v240
	v_cndmask_b32_e64 v236, v236, v237, s[98:99]
	global_store_dword v[234:235], v236, off offset:1568
	v_mov_b32_dpp v236, v4 row_shl:1 row_mask:0xf bank_mask:0xf
	v_mov_b32_dpp v237, v5 row_shr:1 row_mask:0xf bank_mask:0xf
	v_perm_b32 v236, v236, v4, v240
	v_perm_b32 v237, v5, v237, v240
	v_cndmask_b32_e64 v236, v236, v237, s[98:99]
	global_store_dword v[232:233], v236, off offset:1600
	v_mov_b32_dpp v236, v6 row_shl:1 row_mask:0xf bank_mask:0xf
	v_mov_b32_dpp v237, v7 row_shr:1 row_mask:0xf bank_mask:0xf
	v_perm_b32 v236, v236, v6, v240
	v_perm_b32 v237, v7, v237, v240
	v_cndmask_b32_e64 v236, v236, v237, s[98:99]
	global_store_dword v[234:235], v236, off offset:1600
	v_mov_b32_dpp v236, v0 row_shl:1 row_mask:0xf bank_mask:0xf
	v_mov_b32_dpp v237, v1 row_shr:1 row_mask:0xf bank_mask:0xf
	v_perm_b32 v236, v236, v0, v240
	v_perm_b32 v237, v1, v237, v240
	v_cndmask_b32_e64 v236, v236, v237, s[98:99]
	global_store_dword v[232:233], v236, off offset:1632
	v_mov_b32_dpp v236, v2 row_shl:1 row_mask:0xf bank_mask:0xf
	v_mov_b32_dpp v237, v3 row_shr:1 row_mask:0xf bank_mask:0xf
	v_perm_b32 v236, v236, v2, v240
	v_perm_b32 v237, v3, v237, v240
	v_cndmask_b32_e64 v236, v236, v237, s[98:99]
	global_store_dword v[234:235], v236, off offset:1632
	s_andn2_b64 exec, exec, s[6:7]
	s_cbranch_execnz .LBB0_643

.LBB0_2093:
	v_lshl_add_u64 v[8:9], v[100:101], 0, v[98:99]
	v_add_co_u32_e32 v12, vcc, 0x1b400000, v8
	ds_read_b128 v[0:3], v105
	ds_read_b128 v[4:7], v105 offset:64
	v_addc_co_u32_e32 v13, vcc, 0, v9, vcc
	flat_load_dwordx4 v[8:11], v[12:13] offset:1536
	flat_load_dwordx4 v[32:35], v[12:13] offset:1600
	ds_read_b128 v[12:15], v106
	ds_read_b128 v[16:19], v106 offset:64
	ds_read_b128 v[20:23], v107
	ds_read_b128 v[24:27], v107 offset:64
	ds_read_b128 v[28:31], v108
	ds_read_b128 v[68:71], v108 offset:64
	ds_read_b128 v[36:39], v105 offset:9216
	ds_read_b128 v[112:115], v105 offset:9280
	v_mov_b32_e32 v111, 0
	v_add_u32_e32 v96, s4, v96
	s_waitcnt vmcnt(0) lgkmcnt(0)
	v_mfma_f32_16x16x32_bf16 v[116:119], v[8:11], v[36:39], 0
	ds_read_b128 v[36:39], v105 offset:11520
	ds_read_b128 v[120:123], v105 offset:11584
	s_waitcnt lgkmcnt(1)
	v_mfma_f32_16x16x32_bf16 v[124:127], v[8:11], v[36:39], 0
	ds_read_b128 v[36:39], v105 offset:13824
	ds_read_b128 v[128:131], v105 offset:13888
	s_waitcnt lgkmcnt(1)
	v_mfma_f32_16x16x32_bf16 v[132:135], v[8:11], v[36:39], 0
	ds_read_b128 v[36:39], v105 offset:16128
	ds_read_b128 v[136:139], v105 offset:16192
	s_waitcnt lgkmcnt(1)
	v_mfma_f32_16x16x32_bf16 v[140:143], v[8:11], v[36:39], 0
	ds_read_b128 v[36:39], v105 offset:18432
	ds_read_b128 v[144:147], v105 offset:18496
	s_waitcnt lgkmcnt(1)
	v_mfma_f32_16x16x32_bf16 v[148:151], v[8:11], v[36:39], 0
	ds_read_b128 v[36:39], v105 offset:20736
	ds_read_b128 v[72:75], v105 offset:20800
	s_waitcnt lgkmcnt(1)
	v_mfma_f32_16x16x32_bf16 v[92:95], v[8:11], v[36:39], 0
	ds_read_b128 v[36:39], v105 offset:23040
	ds_read_b128 v[76:79], v105 offset:23104
	s_waitcnt lgkmcnt(1)
	v_mfma_f32_16x16x32_bf16 v[88:91], v[8:11], v[36:39], 0
	ds_read_b128 v[36:39], v105 offset:25344
	ds_read_b128 v[80:83], v105 offset:25408
	v_mfma_f32_16x16x32_bf16 v[0:3], v[8:11], v[0:3], 0
	v_mfma_f32_16x16x32_bf16 v[12:15], v[8:11], v[12:15], 0
	s_waitcnt lgkmcnt(1)
	v_mfma_f32_16x16x32_bf16 v[84:87], v[8:11], v[36:39], 0
	ds_read_b128 v[40:43], v105 offset:27648
	ds_read_b128 v[36:39], v105 offset:27712
	ds_read_b128 v[48:51], v105 offset:29952
	ds_read_b128 v[44:47], v105 offset:30016
	ds_read_b128 v[56:59], v105 offset:32256
	ds_read_b128 v[52:55], v105 offset:32320
	v_mfma_f32_16x16x32_bf16 v[20:23], v[8:11], v[20:23], 0
	ds_read_b128 v[64:67], v105 offset:34560
	ds_read_b128 v[60:63], v105 offset:34624
	v_mfma_f32_16x16x32_bf16 v[28:31], v[8:11], v[28:31], 0
	s_waitcnt lgkmcnt(5)
	v_mfma_f32_16x16x32_bf16 v[48:51], v[8:11], v[48:51], 0
	s_waitcnt lgkmcnt(3)
	v_mfma_f32_16x16x32_bf16 v[56:59], v[8:11], v[56:59], 0
	v_mfma_f32_16x16x32_bf16 v[0:3], v[32:35], v[4:7], v[0:3]
	v_mfma_f32_16x16x32_bf16 v[4:7], v[32:35], v[16:19], v[12:15]
	v_mfma_f32_16x16x32_bf16 v[40:43], v[8:11], v[40:43], 0
	s_waitcnt lgkmcnt(1)
	v_mfma_f32_16x16x32_bf16 v[64:67], v[8:11], v[64:67], 0
	v_mfma_f32_16x16x32_bf16 v[8:11], v[32:35], v[24:27], v[20:23]
	v_mfma_f32_16x16x32_bf16 v[12:15], v[32:35], v[68:71], v[28:31]
	v_mfma_f32_16x16x32_bf16 v[16:19], v[32:35], v[112:115], v[116:119]
	v_mov_b32_e32 v114, 0
	v_mov_b32_e32 v113, 0
	v_mov_b32_e32 v112, 0
	v_mfma_f32_16x16x32_bf16 v[20:23], v[32:35], v[120:123], v[124:127]
	v_mov_b32_e32 v118, 0
	v_mov_b32_e32 v119, 0
	v_mov_b32_e32 v117, 0
	v_mfma_f32_16x16x32_bf16 v[24:27], v[32:35], v[128:131], v[132:135]
	v_mov_b32_e32 v116, 0
	v_mov_b32_e32 v115, 0
	v_mfma_f32_16x16x32_bf16 v[28:31], v[32:35], v[136:139], v[140:143]
	v_mfma_f32_16x16x32_bf16 v[44:47], v[32:35], v[44:47], v[48:51]
	v_mfma_f32_16x16x32_bf16 v[48:51], v[32:35], v[52:55], v[56:59]
	v_max_f32_e32 v52, v4, v4
	v_max_f32_e32 v53, v0, v0
	v_max_f32_e32 v54, v5, v5
	v_max_f32_e32 v55, v1, v1
	v_max_f32_e32 v56, v6, v6
	v_max_f32_e32 v57, v2, v2
	v_max_f32_e32 v58, v7, v7
	v_max_f32_e32 v59, v3, v3
	v_mfma_f32_16x16x32_bf16 v[68:71], v[32:35], v[144:147], v[148:151]
	v_max_f32_e32 v52, v53, v52
	v_max_f32_e32 v53, v55, v54
	v_max_f32_e32 v54, v57, v56
	v_mfma_f32_16x16x32_bf16 v[72:75], v[32:35], v[72:75], v[92:95]
	v_max_f32_e32 v55, v59, v58
	v_max3_f32 v52, v52, v8, v12
	v_max3_f32 v53, v53, v9, v13
	v_mfma_f32_16x16x32_bf16 v[76:79], v[32:35], v[76:79], v[88:91]
	v_max3_f32 v54, v54, v10, v14
	v_max3_f32 v55, v55, v11, v15
	v_max3_f32 v52, v52, v16, v20
	v_mfma_f32_16x16x32_bf16 v[80:83], v[32:35], v[80:83], v[84:87]
	v_max3_f32 v53, v53, v17, v21
	v_max3_f32 v54, v54, v18, v22
	v_max3_f32 v55, v55, v19, v23
	v_mfma_f32_16x16x32_bf16 v[40:43], v[32:35], v[36:39], v[40:43]
	v_max3_f32 v52, v52, v24, v28
	v_max3_f32 v53, v53, v25, v29
	v_max3_f32 v54, v54, v26, v30
	s_waitcnt lgkmcnt(0)
	v_mfma_f32_16x16x32_bf16 v[32:35], v[32:35], v[60:63], v[64:67]
	v_max3_f32 v55, v55, v27, v31
	v_max3_f32 v52, v52, v68, v72
	v_max3_f32 v53, v53, v69, v73
	v_max3_f32 v54, v54, v70, v74
	v_max3_f32 v55, v55, v71, v75
	v_max3_f32 v52, v52, v76, v80
	v_max3_f32 v53, v53, v77, v81
	v_max3_f32 v54, v54, v78, v82
	v_max3_f32 v55, v55, v79, v83
	v_max3_f32 v52, v52, v40, v44
	v_max3_f32 v53, v53, v41, v45
	v_max3_f32 v54, v54, v42, v46
	v_max3_f32 v55, v55, v43, v47
	v_mov_b32_e32 v88, 0
	v_max3_f32 v52, v52, v48, v32
	v_max3_f32 v53, v53, v49, v33
	v_max3_f32 v54, v54, v50, v34
	v_max3_f32 v55, v55, v51, v35
	v_mov_b32_dpp v114, v52 row_ror:8 row_mask:0xf bank_mask:0xf
	v_mov_b32_dpp v118, v53 row_ror:8 row_mask:0xf bank_mask:0xf
	v_mov_b32_dpp v119, v54 row_ror:8 row_mask:0xf bank_mask:0xf
	v_mov_b32_dpp v88, v55 row_ror:8 row_mask:0xf bank_mask:0xf
	v_max_f32_e32 v56, v114, v114
	v_max_f32_e32 v57, v118, v118
	v_max_f32_e32 v58, v119, v119
	v_max_f32_e32 v59, v88, v88
	v_mov_b32_e32 v92, 0
	v_mov_b32_e32 v89, 0
	v_max_f32_e32 v52, v52, v56
	v_max_f32_e32 v53, v53, v57
	v_max_f32_e32 v54, v54, v58
	v_max_f32_e32 v55, v55, v59
	v_mov_b32_dpp v113, v52 row_ror:4 row_mask:0xf bank_mask:0xf
	v_mov_b32_dpp v117, v53 row_ror:4 row_mask:0xf bank_mask:0xf
	v_mov_b32_dpp v92, v54 row_ror:4 row_mask:0xf bank_mask:0xf
	v_mov_b32_dpp v89, v55 row_ror:4 row_mask:0xf bank_mask:0xf
	v_max_f32_e32 v56, v113, v113
	v_max_f32_e32 v57, v117, v117
	v_max_f32_e32 v58, v92, v92
	v_max_f32_e32 v59, v89, v89
	v_mov_b32_e32 v93, 0
	v_mov_b32_e32 v90, 0
	v_max_f32_e32 v52, v52, v56
	v_max_f32_e32 v53, v53, v57
	v_max_f32_e32 v54, v54, v58
	v_max_f32_e32 v55, v55, v59
	v_mov_b32_dpp v112, v52 row_ror:2 row_mask:0xf bank_mask:0xf
	v_mov_b32_dpp v116, v53 row_ror:2 row_mask:0xf bank_mask:0xf
	v_mov_b32_dpp v93, v54 row_ror:2 row_mask:0xf bank_mask:0xf
	v_mov_b32_dpp v90, v55 row_ror:2 row_mask:0xf bank_mask:0xf
	v_max_f32_e32 v56, v112, v112
	v_max_f32_e32 v57, v116, v116
	v_max_f32_e32 v58, v93, v93
	v_max_f32_e32 v59, v90, v90
	v_mov_b32_e32 v94, 0
	v_mov_b32_e32 v86, 0
	v_max_f32_e32 v52, v52, v56
	v_max_f32_e32 v53, v53, v57
	v_max_f32_e32 v54, v54, v58
	v_max_f32_e32 v55, v55, v59
	v_mov_b32_dpp v111, v52 row_ror:1 row_mask:0xf bank_mask:0xf
	v_mov_b32_dpp v115, v53 row_ror:1 row_mask:0xf bank_mask:0xf
	v_mov_b32_dpp v94, v54 row_ror:1 row_mask:0xf bank_mask:0xf
	v_mov_b32_dpp v86, v55 row_ror:1 row_mask:0xf bank_mask:0xf
	v_max_f32_e32 v56, v111, v111
	v_max_f32_e32 v57, v115, v115
	v_max_f32_e32 v58, v94, v94
	v_max_f32_e32 v59, v86, v86
	v_max_f32_e32 v52, v52, v56
	v_max_f32_e32 v53, v53, v57
	v_max_f32_e32 v54, v54, v58
	v_max_f32_e32 v55, v55, v59
	v_sub_f32_e32 v0, v0, v52
	v_sub_f32_e32 v4, v4, v52
	v_sub_f32_e32 v8, v8, v52
	v_sub_f32_e32 v12, v12, v52
	v_sub_f32_e32 v16, v16, v52
	v_sub_f32_e32 v20, v20, v52
	v_sub_f32_e32 v24, v24, v52
	v_sub_f32_e32 v28, v28, v52
	v_sub_f32_e32 v56, v68, v52
	v_sub_f32_e32 v57, v72, v52
	v_sub_f32_e32 v58, v76, v52
	v_sub_f32_e32 v59, v80, v52
	v_sub_f32_e32 v40, v40, v52
	v_sub_f32_e32 v44, v44, v52
	v_sub_f32_e32 v48, v48, v52
	v_sub_f32_e32 v32, v32, v52
	v_sub_f32_e32 v1, v1, v53
	v_sub_f32_e32 v5, v5, v53
	v_sub_f32_e32 v9, v9, v53
	v_sub_f32_e32 v13, v13, v53
	v_sub_f32_e32 v17, v17, v53
	v_sub_f32_e32 v21, v21, v53
	v_sub_f32_e32 v29, v29, v53
	v_sub_f32_e32 v52, v69, v53
	v_sub_f32_e32 v60, v73, v53
	v_sub_f32_e32 v61, v77, v53
	v_sub_f32_e32 v62, v81, v53
	v_sub_f32_e32 v41, v41, v53
	v_sub_f32_e32 v45, v45, v53
	v_sub_f32_e32 v33, v33, v53
	v_sub_f32_e32 v2, v2, v54
	v_sub_f32_e32 v10, v10, v54
	v_sub_f32_e32 v18, v18, v54
	v_sub_f32_e32 v22, v22, v54
	v_sub_f32_e32 v63, v74, v54
	v_sub_f32_e32 v64, v78, v54
	v_sub_f32_e32 v65, v82, v54
	v_sub_f32_e32 v3, v3, v55
	v_sub_f32_e32 v11, v11, v55
	v_sub_f32_e32 v25, v25, v53
	v_sub_f32_e32 v49, v49, v53
	v_sub_f32_e32 v6, v6, v54
	v_sub_f32_e32 v14, v14, v54
	v_sub_f32_e32 v26, v26, v54
	v_sub_f32_e32 v30, v30, v54
	v_sub_f32_e32 v53, v70, v54
	v_sub_f32_e32 v42, v42, v54
	v_sub_f32_e32 v46, v46, v54
	v_sub_f32_e32 v50, v50, v54
	v_sub_f32_e32 v34, v34, v54
	v_sub_f32_e32 v7, v7, v55
	v_sub_f32_e32 v15, v15, v55
	v_sub_f32_e32 v19, v19, v55
	v_sub_f32_e32 v23, v23, v55
	v_sub_f32_e32 v27, v27, v55
	v_sub_f32_e32 v31, v31, v55
	v_sub_f32_e32 v54, v71, v55
	v_sub_f32_e32 v66, v75, v55
	v_sub_f32_e32 v67, v79, v55
	v_sub_f32_e32 v68, v83, v55
	v_sub_f32_e32 v43, v43, v55
	v_sub_f32_e32 v47, v47, v55
	v_sub_f32_e32 v51, v51, v55
	v_sub_f32_e32 v35, v35, v55
	v_mul_f32_e32 v0, 0x3fb8aa3b, v0
	v_mul_f32_e32 v4, 0x3fb8aa3b, v4
	v_mul_f32_e32 v8, 0x3fb8aa3b, v8
	v_mul_f32_e32 v12, 0x3fb8aa3b, v12
	v_mul_f32_e32 v16, 0x3fb8aa3b, v16
	v_mul_f32_e32 v20, 0x3fb8aa3b, v20
	v_mul_f32_e32 v24, 0x3fb8aa3b, v24
	v_mul_f32_e32 v28, 0x3fb8aa3b, v28
	v_mul_f32_e32 v55, 0x3fb8aa3b, v56
	v_mul_f32_e32 v56, 0x3fb8aa3b, v57
	v_mul_f32_e32 v57, 0x3fb8aa3b, v58
	v_mul_f32_e32 v58, 0x3fb8aa3b, v59
	v_mul_f32_e32 v40, 0x3fb8aa3b, v40
	v_mul_f32_e32 v44, 0x3fb8aa3b, v44
	v_mul_f32_e32 v48, 0x3fb8aa3b, v48
	v_mul_f32_e32 v32, 0x3fb8aa3b, v32
	v_mul_f32_e32 v1, 0x3fb8aa3b, v1
	v_mul_f32_e32 v5, 0x3fb8aa3b, v5
	v_mul_f32_e32 v9, 0x3fb8aa3b, v9
	v_mul_f32_e32 v13, 0x3fb8aa3b, v13
	v_mul_f32_e32 v17, 0x3fb8aa3b, v17
	v_mul_f32_e32 v21, 0x3fb8aa3b, v21
	v_mul_f32_e32 v29, 0x3fb8aa3b, v29
	v_mul_f32_e32 v52, 0x3fb8aa3b, v52
	v_mul_f32_e32 v59, 0x3fb8aa3b, v60
	v_mul_f32_e32 v60, 0x3fb8aa3b, v61
	v_mul_f32_e32 v61, 0x3fb8aa3b, v62
	v_mul_f32_e32 v41, 0x3fb8aa3b, v41
	v_mul_f32_e32 v45, 0x3fb8aa3b, v45
	v_mul_f32_e32 v33, 0x3fb8aa3b, v33
	v_mul_f32_e32 v2, 0x3fb8aa3b, v2
	v_mul_f32_e32 v10, 0x3fb8aa3b, v10
	v_mul_f32_e32 v18, 0x3fb8aa3b, v18
	v_mul_f32_e32 v22, 0x3fb8aa3b, v22
	v_mul_f32_e32 v62, 0x3fb8aa3b, v63
	v_mul_f32_e32 v63, 0x3fb8aa3b, v64
	v_mul_f32_e32 v64, 0x3fb8aa3b, v65
	v_mul_f32_e32 v3, 0x3fb8aa3b, v3
	v_mul_f32_e32 v11, 0x3fb8aa3b, v11
	v_mul_f32_e32 v25, 0x3fb8aa3b, v25
	v_mul_f32_e32 v49, 0x3fb8aa3b, v49
	v_mul_f32_e32 v6, 0x3fb8aa3b, v6
	v_mul_f32_e32 v14, 0x3fb8aa3b, v14
	v_mul_f32_e32 v26, 0x3fb8aa3b, v26
	v_mul_f32_e32 v30, 0x3fb8aa3b, v30
	v_mul_f32_e32 v53, 0x3fb8aa3b, v53
	v_mul_f32_e32 v42, 0x3fb8aa3b, v42
	v_mul_f32_e32 v46, 0x3fb8aa3b, v46
	v_mul_f32_e32 v50, 0x3fb8aa3b, v50
	v_mul_f32_e32 v34, 0x3fb8aa3b, v34
	v_mul_f32_e32 v7, 0x3fb8aa3b, v7
	v_mul_f32_e32 v15, 0x3fb8aa3b, v15
	v_mul_f32_e32 v19, 0x3fb8aa3b, v19
	v_mul_f32_e32 v23, 0x3fb8aa3b, v23
	v_mul_f32_e32 v27, 0x3fb8aa3b, v27
	v_mul_f32_e32 v31, 0x3fb8aa3b, v31
	v_mul_f32_e32 v54, 0x3fb8aa3b, v54
	v_mul_f32_e32 v65, 0x3fb8aa3b, v66
	v_mul_f32_e32 v66, 0x3fb8aa3b, v67
	v_mul_f32_e32 v67, 0x3fb8aa3b, v68
	v_mul_f32_e32 v43, 0x3fb8aa3b, v43
	v_mul_f32_e32 v47, 0x3fb8aa3b, v47
	v_mul_f32_e32 v51, 0x3fb8aa3b, v51
	v_mul_f32_e32 v35, 0x3fb8aa3b, v35
	v_exp_f32_e32 v0, v0
	v_exp_f32_e32 v4, v4
	v_exp_f32_e32 v8, v8
	v_exp_f32_e32 v12, v12
	v_exp_f32_e32 v111, v16
	v_exp_f32_e32 v156, v20
	v_exp_f32_e32 v157, v24
	v_exp_f32_e32 v158, v28
	v_exp_f32_e32 v159, v55
	v_exp_f32_e32 v160, v56
	v_exp_f32_e32 v161, v57
	v_exp_f32_e32 v162, v58
	v_exp_f32_e32 v163, v40
	v_exp_f32_e32 v164, v44
	v_exp_f32_e32 v165, v48
	v_exp_f32_e32 v166, v32
	v_exp_f32_e32 v1, v1
	v_exp_f32_e32 v5, v5
	v_exp_f32_e32 v9, v9
	v_exp_f32_e32 v13, v13
	v_exp_f32_e32 v167, v17
	v_exp_f32_e32 v168, v21
	v_exp_f32_e32 v170, v29
	v_exp_f32_e32 v171, v52
	v_exp_f32_e32 v172, v59
	v_exp_f32_e32 v174, v61
	v_exp_f32_e32 v175, v41
	v_exp_f32_e32 v177, v45
	v_exp_f32_e32 v179, v33
	v_exp_f32_e32 v2, v2
	v_exp_f32_e32 v10, v10
	v_exp_f32_e32 v180, v18
	v_exp_f32_e32 v181, v22
	v_exp_f32_e32 v186, v63
	v_exp_f32_e32 v187, v64
	v_exp_f32_e32 v3, v3
	v_exp_f32_e32 v11, v11
	v_lshl_add_u64 v[84:85], v[100:101], 0, v[102:103]
	v_exp_f32_e32 v169, v25
	v_exp_f32_e32 v173, v60
	v_exp_f32_e32 v178, v49
	v_exp_f32_e32 v6, v6
	v_exp_f32_e32 v14, v14
	v_exp_f32_e32 v182, v26
	v_exp_f32_e32 v183, v30
	v_exp_f32_e32 v184, v53
	v_exp_f32_e32 v185, v62
	v_exp_f32_e32 v188, v42
	v_exp_f32_e32 v189, v46
	v_exp_f32_e32 v190, v50
	v_exp_f32_e32 v191, v34
	v_exp_f32_e32 v7, v7
	v_exp_f32_e32 v15, v15
	v_exp_f32_e32 v192, v19
	v_exp_f32_e32 v193, v23
	v_exp_f32_e32 v194, v27
	v_exp_f32_e32 v195, v31
	v_exp_f32_e32 v196, v54
	v_exp_f32_e32 v197, v65
	v_exp_f32_e32 v198, v66
	v_exp_f32_e32 v199, v67
	v_exp_f32_e32 v200, v43
	v_exp_f32_e32 v201, v47
	v_exp_f32_e32 v202, v51
	v_exp_f32_e32 v203, v35
	v_add_co_u32_e32 v36, vcc, s5, v84
	v_add_f32_e32 v16, 0, v0
	s_nop 0
	v_addc_co_u32_e32 v37, vcc, 0, v85, vcc
	v_add_co_u32_e32 v38, vcc, s11, v84
	v_bfe_u32 v17, v0, 16, 1
	v_bfe_u32 v18, v4, 16, 1
	v_bfe_u32 v19, v8, 16, 1
	v_bfe_u32 v20, v12, 16, 1
	v_bfe_u32 v21, v111, 16, 1
	v_bfe_u32 v22, v156, 16, 1
	v_bfe_u32 v23, v157, 16, 1
	v_bfe_u32 v24, v158, 16, 1
	v_bfe_u32 v25, v159, 16, 1
	v_bfe_u32 v26, v160, 16, 1
	v_bfe_u32 v27, v161, 16, 1
	v_bfe_u32 v28, v162, 16, 1
	v_bfe_u32 v29, v163, 16, 1
	v_bfe_u32 v30, v164, 16, 1
	v_bfe_u32 v31, v165, 16, 1
	v_bfe_u32 v32, v166, 16, 1
	v_add_f32_e32 v33, 0, v1
	v_bfe_u32 v34, v1, 16, 1
	v_bfe_u32 v35, v5, 16, 1
	v_bfe_u32 v40, v9, 16, 1
	v_bfe_u32 v41, v13, 16, 1
	v_bfe_u32 v42, v167, 16, 1
	v_bfe_u32 v43, v168, 16, 1
	v_bfe_u32 v45, v170, 16, 1
	v_bfe_u32 v46, v171, 16, 1
	v_bfe_u32 v47, v172, 16, 1
	v_bfe_u32 v49, v174, 16, 1
	v_bfe_u32 v50, v175, 16, 1
	v_bfe_u32 v51, v177, 16, 1
	v_bfe_u32 v53, v179, 16, 1
	v_add_f32_e32 v54, 0, v2
	v_bfe_u32 v55, v2, 16, 1
	v_bfe_u32 v57, v10, 16, 1
	v_bfe_u32 v59, v180, 16, 1
	v_bfe_u32 v60, v181, 16, 1
	v_bfe_u32 v65, v186, 16, 1
	v_bfe_u32 v66, v187, 16, 1
	v_add_f32_e32 v71, 0, v3
	v_bfe_u32 v72, v3, 16, 1
	v_bfe_u32 v74, v11, 16, 1
	v_addc_co_u32_e32 v39, vcc, 0, v85, vcc
	v_bfe_u32 v44, v169, 16, 1
	v_bfe_u32 v48, v173, 16, 1
	v_bfe_u32 v52, v178, 16, 1
	v_bfe_u32 v56, v6, 16, 1
	v_bfe_u32 v58, v14, 16, 1
	v_bfe_u32 v61, v182, 16, 1
	v_bfe_u32 v62, v183, 16, 1
	v_bfe_u32 v63, v184, 16, 1
	v_bfe_u32 v64, v185, 16, 1
	v_bfe_u32 v67, v188, 16, 1
	v_bfe_u32 v68, v189, 16, 1
	v_bfe_u32 v69, v190, 16, 1
	v_bfe_u32 v70, v191, 16, 1
	v_bfe_u32 v73, v7, 16, 1
	v_bfe_u32 v75, v15, 16, 1
	v_bfe_u32 v76, v192, 16, 1
	v_bfe_u32 v77, v193, 16, 1
	v_bfe_u32 v78, v194, 16, 1
	v_bfe_u32 v79, v195, 16, 1
	v_bfe_u32 v80, v196, 16, 1
	v_bfe_u32 v81, v197, 16, 1
	v_bfe_u32 v82, v198, 16, 1
	v_bfe_u32 v83, v199, 16, 1
	v_bfe_u32 v84, v200, 16, 1
	v_bfe_u32 v85, v201, 16, 1
	v_bfe_u32 v86, v202, 16, 1
	v_bfe_u32 v87, v203, 16, 1
	v_add3_u32 v0, v0, v17, s10
	v_add_f32_e32 v16, v4, v16
	v_add3_u32 v4, v4, v18, s10
	v_add3_u32 v17, v8, v19, s10
	v_add3_u32 v18, v12, v20, s10
	v_add3_u32 v19, v111, v21, s10
	v_add3_u32 v20, v156, v22, s10
	v_add3_u32 v21, v157, v23, s10
	v_add3_u32 v22, v158, v24, s10
	v_add3_u32 v23, v159, v25, s10
	v_add3_u32 v24, v160, v26, s10
	v_add3_u32 v25, v161, v27, s10
	v_add3_u32 v26, v162, v28, s10
	v_add3_u32 v27, v163, v29, s10
	v_add3_u32 v28, v164, v30, s10
	v_add3_u32 v29, v165, v31, s10
	v_add3_u32 v30, v166, v32, s10
	v_add3_u32 v1, v1, v34, s10
	v_add_f32_e32 v31, v5, v33
	v_add3_u32 v5, v5, v35, s10
	v_add3_u32 v32, v9, v40, s10
	v_add3_u32 v33, v13, v41, s10
	v_add3_u32 v34, v167, v42, s10
	v_add3_u32 v35, v168, v43, s10
	v_add3_u32 v41, v170, v45, s10
	v_add3_u32 v42, v171, v46, s10
	v_add3_u32 v43, v172, v47, s10
	v_add3_u32 v45, v174, v49, s10
	v_add3_u32 v46, v175, v50, s10
	v_add3_u32 v47, v177, v51, s10
	v_add3_u32 v49, v179, v53, s10
	v_add3_u32 v2, v2, v55, s10
	v_add_f32_e32 v50, v6, v54
	v_add3_u32 v51, v10, v57, s10
	v_add3_u32 v53, v180, v59, s10
	v_add3_u32 v54, v181, v60, s10
	v_add3_u32 v59, v186, v65, s10
	v_add3_u32 v60, v187, v66, s10
	v_add3_u32 v3, v3, v72, s10
	v_add_f32_e32 v65, v7, v71
	v_add3_u32 v66, v11, v74, s10
	v_add3_u32 v40, v169, v44, s10
	v_add3_u32 v44, v173, v48, s10
	v_add3_u32 v48, v178, v52, s10
	v_add3_u32 v6, v6, v56, s10
	v_add3_u32 v52, v14, v58, s10
	v_add3_u32 v55, v182, v61, s10
	v_add3_u32 v56, v183, v62, s10
	v_add3_u32 v57, v184, v63, s10
	v_add3_u32 v58, v185, v64, s10
	v_add3_u32 v61, v188, v67, s10
	v_add3_u32 v62, v189, v68, s10
	v_add3_u32 v63, v190, v69, s10
	v_add3_u32 v64, v191, v70, s10
	v_add3_u32 v7, v7, v73, s10
	v_add3_u32 v67, v15, v75, s10
	v_add3_u32 v68, v192, v76, s10
	v_add3_u32 v69, v193, v77, s10
	v_add3_u32 v70, v194, v78, s10
	v_add3_u32 v71, v195, v79, s10
	v_add3_u32 v72, v196, v80, s10
	v_add3_u32 v73, v197, v81, s10
	v_add3_u32 v74, v198, v82, s10
	v_add3_u32 v75, v199, v83, s10
	v_add3_u32 v76, v200, v84, s10
	v_add3_u32 v77, v201, v85, s10
	v_add3_u32 v78, v202, v86, s10
	v_add3_u32 v79, v203, v87, s10
	ds_write_b16_d16_hi v109, v0
	ds_write_b16_d16_hi v109, v4 offset:32
	v_add_f32_e32 v0, v8, v16
	ds_write_b16_d16_hi v109, v17 offset:64
	ds_write_b16_d16_hi v109, v18 offset:96
	ds_write_b16_d16_hi v109, v19 offset:128
	ds_write_b16_d16_hi v109, v20 offset:160
	ds_write_b16_d16_hi v109, v21 offset:192
	ds_write_b16_d16_hi v109, v22 offset:224
	ds_write_b16_d16_hi v109, v23 offset:256
	ds_write_b16_d16_hi v109, v24 offset:288
	ds_write_b16_d16_hi v109, v25 offset:320
	ds_write_b16_d16_hi v109, v26 offset:352
	ds_write_b16_d16_hi v109, v27 offset:384
	ds_write_b16_d16_hi v109, v28 offset:416
	ds_write_b16_d16_hi v109, v29 offset:448
	ds_write_b16_d16_hi v109, v30 offset:480
	ds_write_b16_d16_hi v109, v1 offset:528
	ds_write_b16_d16_hi v109, v5 offset:560
	v_add_f32_e32 v1, v9, v31
	ds_write_b16_d16_hi v109, v32 offset:592
	ds_write_b16_d16_hi v109, v33 offset:624
	ds_write_b16_d16_hi v109, v34 offset:656
	ds_write_b16_d16_hi v109, v35 offset:688
	ds_write_b16_d16_hi v109, v40 offset:720
	ds_write_b16_d16_hi v109, v41 offset:752
	ds_write_b16_d16_hi v109, v42 offset:784
	ds_write_b16_d16_hi v109, v43 offset:816
	ds_write_b16_d16_hi v109, v44 offset:848
	ds_write_b16_d16_hi v109, v45 offset:880
	ds_write_b16_d16_hi v109, v46 offset:912
	ds_write_b16_d16_hi v109, v47 offset:944
	ds_write_b16_d16_hi v109, v48 offset:976
	ds_write_b16_d16_hi v109, v49 offset:1008
	ds_write_b16_d16_hi v109, v2 offset:1056
	ds_write_b16_d16_hi v109, v6 offset:1088
	v_add_f32_e32 v2, v10, v50
	ds_write_b16_d16_hi v109, v51 offset:1120
	ds_write_b16_d16_hi v109, v52 offset:1152
	ds_write_b16_d16_hi v109, v53 offset:1184
	ds_write_b16_d16_hi v109, v54 offset:1216
	ds_write_b16_d16_hi v109, v55 offset:1248
	ds_write_b16_d16_hi v109, v56 offset:1280
	ds_write_b16_d16_hi v109, v57 offset:1312
	ds_write_b16_d16_hi v109, v58 offset:1344
	ds_write_b16_d16_hi v109, v59 offset:1376
	ds_write_b16_d16_hi v109, v60 offset:1408
	ds_write_b16_d16_hi v109, v61 offset:1440
	ds_write_b16_d16_hi v109, v62 offset:1472
	ds_write_b16_d16_hi v109, v63 offset:1504
	ds_write_b16_d16_hi v109, v64 offset:1536
	ds_write_b16_d16_hi v109, v3 offset:1584
	ds_write_b16_d16_hi v109, v7 offset:1616
	v_add_f32_e32 v3, v11, v65
	ds_write_b16_d16_hi v109, v66 offset:1648
	ds_write_b16_d16_hi v109, v67 offset:1680
	ds_write_b16_d16_hi v109, v68 offset:1712
	ds_write_b16_d16_hi v109, v69 offset:1744
	ds_write_b16_d16_hi v109, v70 offset:1776
	ds_write_b16_d16_hi v109, v71 offset:1808
	ds_write_b16_d16_hi v109, v72 offset:1840
	ds_write_b16_d16_hi v109, v73 offset:1872
	ds_write_b16_d16_hi v109, v74 offset:1904
	ds_write_b16_d16_hi v109, v75 offset:1936
	ds_write_b16_d16_hi v109, v76 offset:1968
	ds_write_b16_d16_hi v109, v77 offset:2000
	ds_write_b16_d16_hi v109, v78 offset:2032
	ds_write_b16_d16_hi v109, v79 offset:2064
	v_add_f32_e32 v204, v12, v0
	v_add_f32_e32 v205, v13, v1
	v_add_f32_e32 v206, v14, v2
	v_add_f32_e32 v207, v15, v3
	ds_read_b128 v[0:3], v104
	ds_read_b128 v[4:7], v104 offset:64
	ds_read_b128 v[8:11], v97 offset:36864
	ds_read_b128 v[12:15], v97 offset:36928
	ds_read_b128 v[16:19], v110 offset:36864
	ds_read_b128 v[20:23], v110 offset:36928
	ds_read_b128 v[24:27], v110 offset:45312
	ds_read_b128 v[28:31], v110 offset:45376
	ds_read_b128 v[32:35], v110 offset:53760
	ds_read_b128 v[40:43], v110 offset:53824
	ds_read_b128 v[44:47], v110 offset:36992
	ds_read_b128 v[48:51], v110 offset:53888
	ds_read_b128 v[52:55], v104 offset:128
	ds_read_b128 v[56:59], v104 offset:192
	ds_read_b128 v[60:63], v97 offset:36992
	ds_read_b128 v[64:67], v97 offset:37056
	s_waitcnt lgkmcnt(13)
	v_mfma_f32_16x16x32_bf16 v[8:11], v[0:3], v[8:11], 0
	ds_read_b128 v[68:71], v110 offset:37056
	ds_read_b128 v[72:75], v110 offset:45440
	ds_read_b128 v[76:79], v110 offset:45504
	ds_read_b128 v[80:83], v110 offset:53952
	ds_read_b128 v[84:87], v104 offset:256
	ds_read_b128 v[88:91], v110 offset:37120
	ds_read_b128 v[92:95], v104 offset:320
	ds_read_b128 v[112:115], v97 offset:37120
	ds_read_b128 v[116:119], v97 offset:37184
	s_waitcnt lgkmcnt(14)
	v_mfma_f32_16x16x32_bf16 v[16:19], v[0:3], v[16:19], 0
	v_cmp_lt_i32_e32 vcc, s12, v96
	v_lshl_add_u64 v[100:101], v[100:101], 0, s[2:3]
	s_or_b64 s[8:9], vcc, s[8:9]
	v_mfma_f32_16x16x32_bf16 v[24:27], v[0:3], v[24:27], 0
	v_mfma_f32_16x16x32_bf16 v[0:3], v[0:3], v[32:35], 0
	ds_read_b128 v[32:35], v110 offset:37184
	ds_read_b128 v[120:123], v110 offset:45568
	ds_read_b128 v[124:127], v110 offset:45632
	v_mfma_f32_16x16x32_bf16 v[8:11], v[4:7], v[12:15], v[8:11]
	ds_read_b128 v[12:15], v110 offset:54016
	ds_read_b128 v[128:131], v110 offset:54080
	ds_read_b128 v[132:135], v97 offset:37248
	v_mfma_f32_16x16x32_bf16 v[16:19], v[4:7], v[20:23], v[16:19]
	ds_read_b128 v[20:23], v110 offset:45696
	ds_read_b128 v[136:139], v104 offset:384
	ds_read_b128 v[140:143], v104 offset:448
	v_mfma_f32_16x16x32_bf16 v[24:27], v[4:7], v[28:31], v[24:27]
	ds_read_b128 v[28:31], v97 offset:37312
	ds_read_b128 v[144:147], v110 offset:37248
	ds_read_b128 v[148:151], v110 offset:37312
	v_mfma_f32_16x16x32_bf16 v[0:3], v[4:7], v[40:43], v[0:3]
	ds_read_b128 v[4:7], v110 offset:45760
	ds_read_b128 v[40:43], v110 offset:54144
	ds_read_b128 v[152:155], v110 offset:54208
	s_waitcnt vmcnt(0)
	s_waitcnt lgkmcnt(14)
	v_mfma_f32_16x16x32_bf16 v[8:11], v[52:55], v[60:63], v[8:11]
	v_add_f32_e32 v60, v111, v204
	v_add_f32_e32 v61, v167, v205
	v_mfma_f32_16x16x32_bf16 v[16:19], v[52:55], v[44:47], v[16:19]
	v_add_f32_e32 v44, v180, v206
	v_add_f32_e32 v45, v192, v207
	v_add_f32_e32 v46, v156, v60
	v_mfma_f32_16x16x32_bf16 v[24:27], v[52:55], v[72:75], v[24:27]
	v_add_f32_e32 v47, v168, v61
	v_add_f32_e32 v44, v181, v44
	v_add_f32_e32 v45, v193, v45
	v_mfma_f32_16x16x32_bf16 v[0:3], v[52:55], v[48:51], v[0:3]
	v_add_f32_e32 v46, v157, v46
	v_add_f32_e32 v47, v169, v47
	v_add_f32_e32 v44, v182, v44
	v_mfma_f32_16x16x32_bf16 v[8:11], v[56:59], v[64:67], v[8:11]
	v_add_f32_e32 v45, v194, v45
	v_add_f32_e32 v46, v158, v46
	v_add_f32_e32 v47, v170, v47
	v_mfma_f32_16x16x32_bf16 v[16:19], v[56:59], v[68:71], v[16:19]
	v_add_f32_e32 v44, v183, v44
	v_add_f32_e32 v45, v195, v45
	v_add_f32_e32 v46, v159, v46
	v_mfma_f32_16x16x32_bf16 v[24:27], v[56:59], v[76:79], v[24:27]
	v_add_f32_e32 v47, v171, v47
	v_add_f32_e32 v44, v184, v44
	v_add_f32_e32 v45, v196, v45
	v_mfma_f32_16x16x32_bf16 v[0:3], v[56:59], v[80:83], v[0:3]
	v_add_f32_e32 v46, v160, v46
	v_add_f32_e32 v47, v172, v47
	v_add_f32_e32 v44, v185, v44
	v_mfma_f32_16x16x32_bf16 v[8:11], v[84:87], v[112:115], v[8:11]
	v_add_f32_e32 v45, v197, v45
	v_add_f32_e32 v46, v161, v46
	v_add_f32_e32 v47, v173, v47
	v_mfma_f32_16x16x32_bf16 v[16:19], v[84:87], v[88:91], v[16:19]
	v_add_f32_e32 v44, v186, v44
	v_add_f32_e32 v45, v198, v45
	v_add_f32_e32 v46, v162, v46
	s_waitcnt lgkmcnt(13)
	v_mfma_f32_16x16x32_bf16 v[24:27], v[84:87], v[120:123], v[24:27]
	v_add_f32_e32 v47, v174, v47
	v_add_f32_e32 v44, v187, v44
	v_add_f32_e32 v45, v199, v45
	s_waitcnt lgkmcnt(11)
	v_mfma_f32_16x16x32_bf16 v[0:3], v[84:87], v[12:15], v[0:3]
	v_add_f32_e32 v12, v163, v46
	v_add_f32_e32 v13, v175, v47
	v_add_f32_e32 v44, v188, v44
	v_mfma_f32_16x16x32_bf16 v[8:11], v[92:95], v[116:119], v[8:11]
	v_add_f32_e32 v45, v200, v45
	v_add_f32_e32 v46, v164, v12
	v_add_f32_e32 v47, v177, v13
	v_mfma_f32_16x16x32_bf16 v[12:15], v[92:95], v[32:35], v[16:19]
	v_add_f32_e32 v32, v189, v44
	v_add_f32_e32 v33, v201, v45
	v_add_f32_e32 v34, v165, v46
	v_mfma_f32_16x16x32_bf16 v[16:19], v[92:95], v[124:127], v[24:27]
	s_waitcnt lgkmcnt(10)
	v_mfma_f32_16x16x32_bf16 v[0:3], v[92:95], v[128:131], v[0:3]
	s_nop 0
	v_add_f32_e32 v24, v178, v47
	v_add_f32_e32 v25, v190, v32
	v_add_f32_e32 v26, v202, v33
	v_add_f32_e32 v27, v166, v34
	v_add_f32_e32 v24, v179, v24
	v_add_f32_e32 v25, v191, v25
	s_waitcnt lgkmcnt(7)
	v_mfma_f32_16x16x32_bf16 v[8:11], v[136:139], v[132:135], v[8:11]
	v_add_f32_e32 v26, v203, v26
	v_add_f32_dpp v27, v27, v27 row_ror:8 row_mask:0xf bank_mask:0xf bound_ctrl:1
	v_add_f32_dpp v24, v24, v24 row_ror:8 row_mask:0xf bank_mask:0xf bound_ctrl:1
	s_waitcnt lgkmcnt(4)
	v_mfma_f32_16x16x32_bf16 v[12:15], v[136:139], v[144:147], v[12:15]
	v_add_f32_dpp v25, v25, v25 row_ror:8 row_mask:0xf bank_mask:0xf bound_ctrl:1
	v_add_f32_dpp v26, v26, v26 row_ror:8 row_mask:0xf bank_mask:0xf bound_ctrl:1
	v_add_f32_dpp v27, v27, v27 row_ror:4 row_mask:0xf bank_mask:0xf bound_ctrl:1
	v_mfma_f32_16x16x32_bf16 v[16:19], v[136:139], v[20:23], v[16:19]
	v_add_f32_dpp v20, v24, v24 row_ror:4 row_mask:0xf bank_mask:0xf bound_ctrl:1
	v_add_f32_dpp v21, v25, v25 row_ror:4 row_mask:0xf bank_mask:0xf bound_ctrl:1
	v_add_f32_dpp v22, v26, v26 row_ror:4 row_mask:0xf bank_mask:0xf bound_ctrl:1
	s_waitcnt lgkmcnt(1)
	v_mfma_f32_16x16x32_bf16 v[0:3], v[136:139], v[40:43], v[0:3]
	v_add_f32_dpp v23, v27, v27 row_ror:2 row_mask:0xf bank_mask:0xf bound_ctrl:1
	v_add_f32_dpp v20, v20, v20 row_ror:2 row_mask:0xf bank_mask:0xf bound_ctrl:1
	v_add_f32_dpp v21, v21, v21 row_ror:2 row_mask:0xf bank_mask:0xf bound_ctrl:1
	v_add_f32_dpp v22, v22, v22 row_ror:2 row_mask:0xf bank_mask:0xf bound_ctrl:1
	v_add_f32_dpp v23, v23, v23 row_ror:1 row_mask:0xf bank_mask:0xf bound_ctrl:1
	v_mfma_f32_16x16x32_bf16 v[8:11], v[140:143], v[28:31], v[8:11]
	v_add_f32_dpp v20, v20, v20 row_ror:1 row_mask:0xf bank_mask:0xf bound_ctrl:1
	v_add_f32_dpp v21, v21, v21 row_ror:1 row_mask:0xf bank_mask:0xf bound_ctrl:1
	v_add_f32_dpp v22, v22, v22 row_ror:1 row_mask:0xf bank_mask:0xf bound_ctrl:1
	v_rcp_f32_e32 v23, v23
	v_mfma_f32_16x16x32_bf16 v[12:15], v[140:143], v[148:151], v[12:15]
	s_nop 2
	v_mul_f32_e32 v8, v23, v8
	v_mfma_f32_16x16x32_bf16 v[4:7], v[140:143], v[4:7], v[16:19]
	s_nop 2
	v_rcp_f32_e32 v16, v20
	v_rcp_f32_e32 v17, v21
	v_rcp_f32_e32 v18, v22
	s_waitcnt lgkmcnt(0)
	v_mfma_f32_16x16x32_bf16 v[0:3], v[140:143], v[152:155], v[0:3]
	v_mul_f32_e32 v9, v16, v9
	v_mul_f32_e32 v10, v17, v10
	v_mul_f32_e32 v11, v18, v11
	v_mul_f32_e32 v12, v23, v12
	v_mul_f32_e32 v13, v16, v13
	v_mul_f32_e32 v14, v17, v14
	v_mul_f32_e32 v15, v18, v15
	v_mul_f32_e32 v4, v23, v4
	v_mul_f32_e32 v5, v16, v5
	v_mul_f32_e32 v6, v17, v6
	v_mul_f32_e32 v7, v18, v7
	v_mul_f32_e32 v0, v23, v0
	v_mul_f32_e32 v1, v16, v1
	v_mul_f32_e32 v2, v17, v2
	v_mul_f32_e32 v3, v18, v3
	v_bfe_u32 v16, v8, 16, 1
	v_bfe_u32 v17, v9, 16, 1
	v_bfe_u32 v18, v10, 16, 1
	v_bfe_u32 v19, v11, 16, 1
	v_bfe_u32 v20, v12, 16, 1
	v_bfe_u32 v21, v13, 16, 1
	v_bfe_u32 v22, v14, 16, 1
	v_bfe_u32 v23, v15, 16, 1
	v_bfe_u32 v24, v4, 16, 1
	v_bfe_u32 v25, v5, 16, 1
	v_bfe_u32 v26, v6, 16, 1
	v_bfe_u32 v27, v7, 16, 1
	v_bfe_u32 v28, v0, 16, 1
	v_bfe_u32 v29, v1, 16, 1
	v_bfe_u32 v30, v2, 16, 1
	v_bfe_u32 v31, v3, 16, 1
	v_add3_u32 v8, v8, v16, s10
	v_add3_u32 v9, v9, v17, s10
	v_add3_u32 v10, v10, v18, s10
	v_add3_u32 v11, v11, v19, s10
	v_add3_u32 v12, v12, v20, s10
	v_add3_u32 v13, v13, v21, s10
	v_add3_u32 v14, v14, v22, s10
	v_add3_u32 v15, v15, v23, s10
	v_add3_u32 v4, v4, v24, s10
	v_add3_u32 v5, v5, v25, s10
	v_add3_u32 v6, v6, v26, s10
	v_add3_u32 v7, v7, v27, s10
	v_add3_u32 v0, v0, v28, s10
	v_add3_u32 v1, v1, v29, s10
	v_add3_u32 v2, v2, v30, s10
	v_add3_u32 v3, v3, v31, s10
	s_mov_b32 s98, 0xaaaaaaaa
	s_mov_b32 s99, 0xaaaaaaaa
	v_mov_b32_e32 v240, 0x7060302
	v_and_b32_e32 v238, 1, v176
	v_mul_u32_u24_e32 v238, 0x7fe, v238
	v_mov_b32_e32 v239, 0
	v_lshl_add_u64 v[232:233], v[36:37], 0, v[238:239]
	v_mov_b32_dpp v236, v8 row_shl:1 row_mask:0xf bank_mask:0xf
	v_mov_b32_dpp v237, v9 row_shr:1 row_mask:0xf bank_mask:0xf
	v_perm_b32 v236, v236, v8, v240
	v_perm_b32 v237, v9, v237, v240
	v_cndmask_b32_e64 v236, v236, v237, s[98:99]
	global_store_dword v[232:233], v236, off offset:1536
	v_lshl_add_u64 v[234:235], v[38:39], 0, v[238:239]
	v_mov_b32_dpp v236, v10 row_shl:1 row_mask:0xf bank_mask:0xf
	v_mov_b32_dpp v237, v11 row_shr:1 row_mask:0xf bank_mask:0xf
	v_perm_b32 v236, v236, v10, v240
	v_perm_b32 v237, v11, v237, v240
	v_cndmask_b32_e64 v236, v236, v237, s[98:99]
	global_store_dword v[234:235], v236, off offset:1536
	v_mov_b32_dpp v236, v12 row_shl:1 row_mask:0xf bank_mask:0xf
	v_mov_b32_dpp v237, v13 row_shr:1 row_mask:0xf bank_mask:0xf
	v_perm_b32 v236, v236, v12, v240
	v_perm_b32 v237, v13, v237, v240
	v_cndmask_b32_e64 v236, v236, v237, s[98:99]
	global_store_dword v[232:233], v236, off offset:1568
	v_mov_b32_dpp v236, v14 row_shl:1 row_mask:0xf bank_mask:0xf
	v_mov_b32_dpp v237, v15 row_shr:1 row_mask:0xf bank_mask:0xf
	v_perm_b32 v236, v236, v14, v240
	v_perm_b32 v237, v15, v237, v240
	v_cndmask_b32_e64 v236, v236, v237, s[98:99]
	global_store_dword v[234:235], v236, off offset:1568
	v_mov_b32_dpp v236, v4 row_shl:1 row_mask:0xf bank_mask:0xf
	v_mov_b32_dpp v237, v5 row_shr:1 row_mask:0xf bank_mask:0xf
	v_perm_b32 v236, v236, v4, v240
	v_perm_b32 v237, v5, v237, v240
	v_cndmask_b32_e64 v236, v236, v237, s[98:99]
	global_store_dword v[232:233], v236, off offset:1600
	v_mov_b32_dpp v236, v6 row_shl:1 row_mask:0xf bank_mask:0xf
	v_mov_b32_dpp v237, v7 row_shr:1 row_mask:0xf bank_mask:0xf
	v_perm_b32 v236, v236, v6, v240
	v_perm_b32 v237, v7, v237, v240
	v_cndmask_b32_e64 v236, v236, v237, s[98:99]
	global_store_dword v[234:235], v236, off offset:1600
	v_mov_b32_dpp v236, v0 row_shl:1 row_mask:0xf bank_mask:0xf
	v_mov_b32_dpp v237, v1 row_shr:1 row_mask:0xf bank_mask:0xf
	v_perm_b32 v236, v236, v0, v240
	v_perm_b32 v237, v1, v237, v240
	v_cndmask_b32_e64 v236, v236, v237, s[98:99]
	global_store_dword v[232:233], v236, off offset:1632
	v_mov_b32_dpp v236, v2 row_shl:1 row_mask:0xf bank_mask:0xf
	v_mov_b32_dpp v237, v3 row_shr:1 row_mask:0xf bank_mask:0xf
	v_perm_b32 v236, v236, v2, v240
	v_perm_b32 v237, v3, v237, v240
	v_cndmask_b32_e64 v236, v236, v237, s[98:99]
	global_store_dword v[234:235], v236, off offset:1632
	s_andn2_b64 exec, exec, s[8:9]
	s_cbranch_execnz .LBB0_2093
